# final rmsnorm fused into the PG epilogue: h3 stays in registers, the four column tiles of a 256-row block meet at a counter, output written from phase 10; phase 11 and its grid barrier removed
# speedup vs baseline: 1.0347x; 1.0347x over previous
; __global__ void __launch_bounds__(512, 2) mega(Params P0) {
;     ...
;     for (int ph = ph_lo; ph <= ph_hi; ++ph) {
;         int tid = threadIdx.x; asm volatile("" : "+v"(tid));
;         int G = gridDim.x, bid = blockIdx.x; asm volatile("" : "+s"(G)); asm volatile("" : "+s"(bid));
;         KArgP kp = (KArgP)__builtin_amdgcn_kernarg_segment_ptr(); asm volatile("" : "+s"(kp));
;         Params P;
; #pragma unroll
;         for (int i = 0; i < 24; ++i) P.in[i] = kp->in[i];
;         P.out = kp->out; P.ws = kp->ws; P.ph_lo = 0; P.ph_hi = 0;
;         unsigned char* dob = (unsigned char*)P.out; unsigned char* ws = P.ws;
;         if (ph == 0) phase0(P, lds, G, bid);
;         else if (ph == 1) { pg8::Gemm g{(const bf16_t*)(dob + DO_ABF), (const bf16_t*)(dob + DO_W1T), NTOK, NPROJ, DM}; pg8::StaticOrder S; S.init(NTOK, NPROJ, G, bid);
;             EpiProj E{(bf16_t*)(ws + WS_PROJ), (const f32x2*)(dob + DO_ROPE), (bf16_t*)(dob + DO_HQ), P.in[6], P.in[7]}; pg8::gemm_phase(lds, g, S, E); }
;         else if (ph == 2) phase_conv(P, G, bid);
;         else if (ph == 3) phase_mix1(P, lds, G, bid);
;         else if (ph == 4) phase_mix2(P, lds, G, bid);
;         else if (ph == 5) {
;             { float* r2 = (float*)(ws + WS_RSS2); for (int i = bid * 512 + tid; i < 2 * NTOK; i += G * 512) r2[i] = 0.f;
;               if (bid == 0 && tid == 0) __hip_atomic_store((unsigned*)(ws + WS_BAR), 0u, __ATOMIC_RELAXED, __HIP_MEMORY_SCOPE_AGENT); }
.LBB0_10:
	v_readlane_b32 s2, v253, 0
	v_mov_b32_e32 v186, v162
	s_mov_b32 s89, s82
	s_mov_b32 s77, s88
	v_readlane_b32 s3, v253, 1
	s_load_dwordx16 s[4:19], s[2:3], 0x0
	s_load_dwordx4 s[20:23], s[2:3], 0xc0
	s_mov_b64 s[56:57], 0
	s_cmp_lt_i32 s80, 3
	s_mov_b64 s[90:91], 0
	s_waitcnt lgkmcnt(0)
	v_writelane_b32 v254, s4, 34
	s_nop 1
	v_writelane_b32 v254, s5, 35
	v_writelane_b32 v254, s6, 36
	v_writelane_b32 v254, s7, 37
	v_writelane_b32 v254, s8, 38
	v_writelane_b32 v254, s9, 39
	v_writelane_b32 v254, s10, 40
	v_writelane_b32 v254, s11, 41
	v_writelane_b32 v254, s12, 42
	v_writelane_b32 v254, s13, 43
	v_writelane_b32 v254, s14, 44
	v_writelane_b32 v254, s15, 45
	v_writelane_b32 v254, s16, 46
	v_writelane_b32 v254, s17, 47
	v_writelane_b32 v254, s18, 48
	v_writelane_b32 v254, s19, 49
	s_load_dwordx16 s[4:19], s[2:3], 0x40
	s_waitcnt lgkmcnt(0)
	v_writelane_b32 v254, s4, 50
	s_nop 1
	v_writelane_b32 v254, s5, 51
	v_writelane_b32 v254, s6, 52
	v_writelane_b32 v254, s7, 53
	v_writelane_b32 v254, s8, 54
	v_writelane_b32 v254, s9, 55
	v_writelane_b32 v254, s10, 56
	v_writelane_b32 v254, s11, 57
	v_writelane_b32 v254, s12, 58
	v_writelane_b32 v254, s13, 59
	v_writelane_b32 v254, s14, 60
	v_writelane_b32 v254, s15, 61
	v_writelane_b32 v254, s16, 62
	v_writelane_b32 v255, s18, 0
	v_writelane_b32 v254, s17, 63
	v_writelane_b32 v255, s19, 1
	s_load_dwordx16 s[4:19], s[2:3], 0x80
	s_mov_b64 s[2:3], -1
	s_waitcnt lgkmcnt(0)
	v_writelane_b32 v255, s4, 2
	s_nop 1
	v_writelane_b32 v255, s5, 3
	v_writelane_b32 v255, s6, 4
	v_writelane_b32 v255, s7, 5
	v_writelane_b32 v255, s8, 6
	v_writelane_b32 v255, s9, 7
	v_writelane_b32 v255, s10, 8
	v_writelane_b32 v255, s11, 9
	v_writelane_b32 v255, s12, 10
	v_writelane_b32 v255, s13, 11
	v_writelane_b32 v255, s14, 12
	v_writelane_b32 v255, s15, 13
	v_writelane_b32 v255, s16, 14
	v_writelane_b32 v255, s17, 15
	v_writelane_b32 v255, s18, 16
	v_writelane_b32 v255, s19, 17
	v_writelane_b32 v255, s89, 18
	v_writelane_b32 v255, s77, 19
	s_cbranch_scc1 .LBB0_573
	s_cmp_gt_i32 s80, 3
	s_cbranch_scc0 .LBB0_372
	s_cmp_gt_i32 s80, 4
	v_writelane_b32 v255, s80, 20
	s_nop 1
	v_writelane_b32 v255, s81, 21
	v_writelane_b32 v255, s82, 22
	v_writelane_b32 v255, s83, 23
	s_cbranch_scc0 .LBB0_69
	s_cmp_eq_u32 s80, 5
	s_mov_b64 s[90:91], -1
	s_cbranch_scc0 .LBB0_68
	s_cmp_lg_u32 s77, 0
	s_cbranch_scc1 .Lpgz_skip
	v_cmp_gt_u32_e32 vcc, 0x80, v186
	s_and_saveexec_b64 s[2:3], vcc
	v_lshlrev_b32_e32 v2, 2, v186
	v_mov_b32_e32 v3, 0
	s_add_u32 s6, s22, 0xd340000
	s_addc_u32 s7, s23, 0
	global_store_dword v2, v3, s[6:7]
	s_or_b64 exec, exec, s[2:3]
.Lpgz_skip:
	v_lshl_add_u32 v2, s77, 9, v186
	s_mov_b32 s0, 0x10000
	v_cmp_gt_i32_e32 vcc, s0, v2
	s_and_saveexec_b64 s[2:3], vcc
	s_movk_i32 s79, 0x3ff0
	s_movk_i32 s83, 0x3fe0
	s_movk_i32 s84, 0x3fd0
	s_movk_i32 s85, 0x3f80
	s_movk_i32 s86, 0x3f70
	s_movk_i32 s87, 0x3f60
	s_movk_i32 s88, 0x3f50
	s_cbranch_execz .LBB0_22
	s_add_u32 s6, s22, 0xd300000
	s_addc_u32 s7, s23, 0
	s_lshl_b32 s4, s89, 9
	v_cvt_f32_u32_e32 v5, s4
	v_add_u32_e32 v3, s4, v2
	v_cmp_gt_i32_e32 vcc, s0, v3
	s_sub_i32 s0, 0, s4
	v_rcp_iflag_f32_e32 v5, v5
	v_max_i32_e32 v0, 0x10000, v3
	v_cndmask_b32_e64 v4, 1, 2, vcc
	v_subb_co_u32_e32 v0, vcc, v0, v3, vcc
	v_mul_f32_e32 v5, 0x4f7ffffe, v5
	v_cvt_u32_f32_e32 v5, v5
	s_mov_b64 s[10:11], -1
	v_mul_lo_u32 v6, s0, v5
	v_mul_hi_u32 v6, v5, v6
	v_add_u32_e32 v5, v5, v6
	v_mul_hi_u32 v5, v0, v5
	v_mul_lo_u32 v6, v5, s4
	v_sub_u32_e32 v0, v0, v6
	v_cmp_le_u32_e32 vcc, s4, v0
	v_add_u32_e32 v6, 1, v5
	s_nop 0
	v_cndmask_b32_e32 v5, v5, v6, vcc
	v_subrev_u32_e32 v6, s4, v0
	v_cndmask_b32_e32 v0, v0, v6, vcc
	v_cmp_le_u32_e32 vcc, s4, v0
	v_add_u32_e32 v0, 1, v5
	s_nop 0
	v_cndmask_b32_e32 v0, v5, v0, vcc
	v_add_u32_e32 v0, v4, v0
	v_cmp_lt_u32_e32 vcc, 1, v0
	s_and_saveexec_b64 s[8:9], vcc
	s_cbranch_execz .LBB0_19
	v_and_b32_e32 v6, -2, v0
	s_lshl_b32 s0, s89, 10
	s_mov_b32 s5, s0
	s_mov_b64 s[10:11], 0
	v_mov_b32_e32 v7, v6
	v_mov_b64_e32 v[4:5], v[2:3]

; __device__ __forceinline__ unsigned cvt_pk_bf16(float lo, float hi) { unsigned r; asm volatile("v_cvt_pk_bf16_f32 %0, %1, %2" : "=v"(r) : "v"(lo), "v"(hi)); return r; }
;     __device__ __forceinline__ void operator()(AccT& acc, const Unit& u, int wr, int wc, int fr, int fq) const {
;     ...
;         bf16_t* base = (u.L < 256 ? T0 : T1) + (size_t)(u.L & 255) * 65536 + (wr * 64 + fr) * 256 + wc * 32 + 8 * fq;
; #pragma unroll
;         for (int ai = 0; ai < 2; ++ai)
; #pragma unroll
;             for (int m = 0; m < 4; ++m) { bf16_t* rowp = base + (ai * 128 + m * 16) * 256;
; #pragma unroll
;                 for (int bj = 0; bj < 2; ++bj) { const f32x4 v0 = acc[ai][bj][m][0], v1 = acc[ai][bj][m][1];
;                     u32x4 w; w.x = cvt_pk_bf16(v0[0], v0[1]); w.y = cvt_pk_bf16(v0[2], v0[3]); w.z = cvt_pk_bf16(v1[0], v1[1]); w.w = cvt_pk_bf16(v1[2], v1[3]);
;                     *(u32x4*)(rowp + bj * 128) = w; } }
.LBB0_738:
	s_and_b32 s14, s78, 7
	s_lshl_b32 s14, s14, 6
	s_lshr_b32 s15, s78, 3
	s_add_i32 s14, s14, s15
	s_lshr_b32 s15, s14, 5
	s_lshl_b32 s15, s15, 3
	s_and_b32 s16, s14, 7
	s_add_i32 s15, s15, s16
	s_lshl_b32 s15, s15, 20
	s_bfe_u32 s16, s14, 0x20003
	s_lshl_b32 s16, s16, 17
	s_add_i32 s16, s16, s15
	s_cmpk_lt_i32 s78, 0x100
	v_mov_b32_e32 v144, v140
	s_cselect_b32 s15, s50, s53
	s_cselect_b32 s14, s51, s52
	v_mov_b32_e32 v146, v141
	s_add_u32 s14, s14, s16
	v_lshl_add_u32 v144, v144, 8, s72
	s_addc_u32 s15, s15, 0
	v_ashrrev_i32_e32 v145, 31, v144
	v_lshl_add_u64 v[144:145], v[144:145], 1, s[14:15]
	v_lshlrev_b32_e32 v146, 3, v146
	v_lshl_add_u64 v[144:145], v[144:145], 0, s[38:39]
	v_ashrrev_i32_e32 v147, 31, v146
	v_lshl_add_u64 v[144:145], v[146:147], 1, v[144:145]
	v_cvt_pk_bf16_f32 v122, v122, v123
	v_cvt_pk_bf16_f32 v123, v124, v125
	v_cvt_pk_bf16_f32 v124, v126, v127
	v_cvt_pk_bf16_f32 v125, v128, v129
	global_store_dwordx4 v[144:145], v[122:125], off
	v_cvt_pk_bf16_f32 v118, v118, v119
	v_cvt_pk_bf16_f32 v119, v120, v121
	v_cvt_pk_bf16_f32 v120, v114, v115
	v_cvt_pk_bf16_f32 v121, v116, v117
	global_store_dwordx4 v[144:145], v[118:121], off offset:256
	v_cvt_pk_bf16_f32 v110, v110, v111
	v_cvt_pk_bf16_f32 v111, v112, v113
	v_cvt_pk_bf16_f32 v112, v106, v107
	v_add_co_u32_e32 v106, vcc, s83, v144
	s_movk_i32 s14, 0x4000
	s_nop 0
	v_addc_co_u32_e32 v107, vcc, 0, v145, vcc
	v_cvt_pk_bf16_f32 v113, v108, v109
	global_store_dwordx4 v[106:107], v[110:113], off
	v_cvt_pk_bf16_f32 v102, v102, v103
	v_cvt_pk_bf16_f32 v103, v104, v105
	v_cvt_pk_bf16_f32 v104, v98, v99
	v_cvt_pk_bf16_f32 v105, v100, v101
	global_store_dwordx4 v[106:107], v[102:105], off offset:256
	v_cvt_pk_bf16_f32 v94, v94, v95
	v_cvt_pk_bf16_f32 v95, v96, v97
	v_cvt_pk_bf16_f32 v96, v90, v91
	v_add_co_u32_e32 v90, vcc, s14, v144
	s_movk_i32 s14, 0x6000
	s_nop 0
	v_addc_co_u32_e32 v91, vcc, 0, v145, vcc
	v_cvt_pk_bf16_f32 v97, v92, v93
	global_store_dwordx4 v[90:91], v[94:97], off
	v_cvt_pk_bf16_f32 v86, v86, v87
	v_cvt_pk_bf16_f32 v87, v88, v89
	v_cvt_pk_bf16_f32 v88, v82, v83
	v_cvt_pk_bf16_f32 v89, v84, v85
	global_store_dwordx4 v[90:91], v[86:89], off offset:256
	v_cvt_pk_bf16_f32 v78, v78, v79
	v_cvt_pk_bf16_f32 v79, v80, v81
	v_cvt_pk_bf16_f32 v80, v74, v75
	v_add_co_u32_e32 v74, vcc, s14, v144
	v_cvt_pk_bf16_f32 v81, v76, v77
	s_mov_b32 s14, 0x12000
	s_nop 0
	v_addc_co_u32_e32 v75, vcc, 0, v145, vcc
	global_store_dwordx4 v[74:75], v[78:81], off
	v_cvt_pk_bf16_f32 v70, v70, v71
	v_cvt_pk_bf16_f32 v71, v72, v73
	v_cvt_pk_bf16_f32 v72, v66, v67
	v_cvt_pk_bf16_f32 v73, v68, v69
	global_store_dwordx4 v[74:75], v[70:73], off offset:256
	v_cvt_pk_bf16_f32 v62, v62, v63
	v_cvt_pk_bf16_f32 v63, v64, v65
	v_cvt_pk_bf16_f32 v64, v58, v59
	v_add_co_u32_e32 v58, vcc, s56, v144
	v_cvt_pk_bf16_f32 v65, v60, v61
	s_mov_b32 s78, s77
	s_nop 0
	v_addc_co_u32_e32 v59, vcc, 0, v145, vcc
	global_store_dwordx4 v[58:59], v[62:65], off
	v_cvt_pk_bf16_f32 v54, v54, v55
	v_cvt_pk_bf16_f32 v55, v56, v57
	v_cvt_pk_bf16_f32 v56, v50, v51
	v_cvt_pk_bf16_f32 v57, v52, v53
	global_store_dwordx4 v[58:59], v[54:57], off offset:256
	v_cvt_pk_bf16_f32 v46, v46, v47
	v_cvt_pk_bf16_f32 v47, v48, v49
	v_cvt_pk_bf16_f32 v48, v42, v43
	v_add_co_u32_e32 v42, vcc, s14, v144
	s_mov_b32 s14, 0x14000
	s_nop 0
	v_addc_co_u32_e32 v43, vcc, 0, v145, vcc
	v_cvt_pk_bf16_f32 v49, v44, v45
	global_store_dwordx4 v[42:43], v[46:49], off
	v_cvt_pk_bf16_f32 v38, v38, v39
	v_cvt_pk_bf16_f32 v39, v40, v41
	v_cvt_pk_bf16_f32 v40, v34, v35
	v_cvt_pk_bf16_f32 v41, v36, v37
	global_store_dwordx4 v[42:43], v[38:41], off offset:256
	v_cvt_pk_bf16_f32 v30, v30, v31
	v_cvt_pk_bf16_f32 v31, v32, v33
	v_cvt_pk_bf16_f32 v32, v26, v27
	v_add_co_u32_e32 v26, vcc, s14, v144
	v_cvt_pk_bf16_f32 v33, v28, v29
	s_mov_b64 s[16:17], s[12:13]
	s_nop 0
	v_addc_co_u32_e32 v27, vcc, 0, v145, vcc
	global_store_dwordx4 v[26:27], v[30:33], off
	v_cvt_pk_bf16_f32 v22, v22, v23
	v_cvt_pk_bf16_f32 v23, v24, v25
	v_cvt_pk_bf16_f32 v24, v18, v19
	v_cvt_pk_bf16_f32 v25, v20, v21
	global_store_dwordx4 v[26:27], v[22:25], off offset:256
	v_cvt_pk_bf16_f32 v14, v14, v15
	v_cvt_pk_bf16_f32 v15, v16, v17
	v_cvt_pk_bf16_f32 v16, v10, v11
	v_add_co_u32_e32 v10, vcc, 0x16000, v144
	s_mov_b64 s[14:15], s[10:11]
	s_nop 0
	v_addc_co_u32_e32 v11, vcc, 0, v145, vcc
	s_and_b64 vcc, exec, s[40:41]
	v_cvt_pk_bf16_f32 v17, v12, v13
	global_store_dwordx4 v[10:11], v[14:17], off
	v_cvt_pk_bf16_f32 v6, v6, v7
	v_cvt_pk_bf16_f32 v7, v8, v9
	v_cvt_pk_bf16_f32 v8, v2, v3
	v_cvt_pk_bf16_f32 v9, v4, v5
	global_store_dwordx4 v[10:11], v[6:9], off offset:256
	s_cbranch_vccnz .LBB0_753

; #define NTL(p) __builtin_nontemporal_load((const f32x4*)(p))
;     __device__ __forceinline__ void operator()(AccT& acc, const Unit& u, int wr, int wc, int fr, int fq) const {
;     ...
;         const int row0 = u.pm * 256 + wr * 64 + fr, col0 = u.pn * 256 + wc * 32 + 8 * fq;
;         f32x4 hv[2][4]; u32x4 pv[2][2]; float rs[2];
;         const bf16_t* ppbase = (u.L < 256 ? T0 : T1) + (size_t)(u.L & 255) * 65536 + (wr * 64 + fr) * 256 + wc * 32 + 8 * fq;
;         { const float* hr = H + (size_t)row0 * DM + col0; const bf16_t* pp = ppbase;
;           hv[0][0] = NTL(hr); hv[0][1] = NTL(hr + 4); hv[0][2] = NTL(hr + 128); hv[0][3] = NTL(hr + 132);
;           pv[0][0] = *(const u32x4*)pp; pv[0][1] = *(const u32x4*)(pp + 128); rs[0] = rss2[row0]; }
; #pragma unroll
;         for (int r = 0; r < 8; ++r) { const int ai = r >> 2, m = r & 3; const int row = row0 + ai * 128 + m * 16;
;             if (r < 7) { const int rn = row0 + ((r + 1) >> 2) * 128 + ((r + 1) & 3) * 16; const float* hn = H + (size_t)rn * DM + col0; const bf16_t* pn = ppbase + (((r + 1) >> 2) * 128 + ((r + 1) & 3) * 16) * 256;
;                 hv[(r + 1) & 1][0] = NTL(hn); hv[(r + 1) & 1][1] = NTL(hn + 4); hv[(r + 1) & 1][2] = NTL(hn + 128); hv[(r + 1) & 1][3] = NTL(hn + 132);
;                 pv[(r + 1) & 1][0] = *(const u32x4*)pn; pv[(r + 1) & 1][1] = *(const u32x4*)(pn + 128); rs[(r + 1) & 1] = rss2[rn]; }
;             float* hp = H + (size_t)row * DM + col0; float ss = 0.f; const float rstd = rsqrtf(rs[r & 1] * (1.0f / DM) + 1e-6f);
.LBB0_781:
	v_add_u32_e32 v205, s79, v169
	v_lshl_add_u32 v186, s0, 8, v205
	s_lshl_b32 s0, s24, 8
	s_or_b32 s0, s0, s80
	s_and_b32 s2, s26, 7
	s_lshl_b32 s2, s2, 6
	s_lshr_b32 s3, s26, 3
	s_add_i32 s2, s2, s3
	s_lshr_b32 s3, s2, 5
	s_lshl_b32 s3, s3, 3
	s_and_b32 s4, s2, 7
	s_add_i32 s3, s3, s4
	s_lshl_b32 s3, s3, 20
	s_bfe_u32 s4, s2, 0x20003
	s_lshl_b32 s4, s4, 17
	s_add_i32 s4, s4, s3
	s_cmpk_lt_i32 s26, 0x100
	s_cselect_b32 s3, s50, s53
	s_cselect_b32 s2, s51, s52
	s_cbranch_scc0 .Lpg_t1sel
	s_lshl_b32 s4, s26, 17
.Lpg_t1sel:
	s_add_u32 s2, s2, s4
	s_addc_u32 s3, s3, 0
	s_add_u32 s2, s2, s38
	s_addc_u32 s3, s3, s39
	v_lshlrev_b32_e32 v201, 9, v205
	v_lshl_add_u32 v201, v222, 4, v201
	v_lshlrev_b32_e32 v204, 3, v222
	v_add_u32_e32 v204, s0, v204
	v_lshlrev_b32_e32 v204, 2, v204
	v_lshl_add_u32 v200, v186, 12, v204
	v_lshlrev_b32_e32 v202, 2, v186
	v_readlane_b32 s72, v255, 14
	v_readlane_b32 s73, v255, 15
	v_readlane_b32 s74, v255, 16
	v_readlane_b32 s75, v255, 17
	v_readfirstlane_b32 s60, v186
	s_nop 3
	global_load_dword v164, v202, s[34:35]
	global_load_dword v165, v202, s[34:35] offset:64
	global_load_dword v166, v202, s[34:35] offset:128
	global_load_dword v167, v202, s[34:35] offset:192
	global_load_dword v170, v202, s[34:35] offset:512
	global_load_dword v171, v202, s[34:35] offset:576
	global_load_dword v172, v202, s[34:35] offset:640
	global_load_dword v173, v202, s[34:35] offset:704
	global_load_dwordx4 v[240:243], v204, s[72:73]
	global_load_dwordx4 v[244:247], v204, s[72:73] offset:16
	global_load_dwordx4 v[248:251], v204, s[72:73] offset:512
	global_load_dwordx4 v[232:235], v204, s[72:73] offset:528
	s_add_u32 s62, s22, 0x0
	s_addc_u32 s63, s23, 0
	global_load_dwordx4 v[130:133], v200, s[62:63] nt
	global_load_dwordx4 v[134:137], v200, s[62:63] offset:16 nt
	global_load_dwordx4 v[138:141], v200, s[62:63] offset:512 nt
	global_load_dwordx4 v[142:145], v200, s[62:63] offset:528 nt
	s_add_u32 s64, s2, 0x0
	s_addc_u32 s65, s3, 0
	global_load_dwordx4 v[146:149], v201, s[64:65]
	global_load_dwordx4 v[150:153], v201, s[64:65] offset:256
	s_add_u32 s62, s22, 0x10000
	s_addc_u32 s63, s23, 0
	global_load_dwordx4 v[184:187], v200, s[62:63] nt
	global_load_dwordx4 v[188:191], v200, s[62:63] offset:16 nt
	global_load_dwordx4 v[192:195], v200, s[62:63] offset:512 nt
	global_load_dwordx4 v[196:199], v200, s[62:63] offset:528 nt
	v_mov_b32_e32 v206, 0xbfb8aa3b
	v_mov_b32_e32 v207, 0xbfb8aa3b
	s_waitcnt vmcnt(14)
	v_fmamk_f32 v164, v164, 0x3a800000, v210
	v_fmamk_f32 v165, v165, 0x3a800000, v210
	v_fmamk_f32 v166, v166, 0x3a800000, v210
	v_fmamk_f32 v167, v167, 0x3a800000, v210
	v_fmamk_f32 v170, v170, 0x3a800000, v210
	v_fmamk_f32 v171, v171, 0x3a800000, v210
	v_fmamk_f32 v172, v172, 0x3a800000, v210
	v_fmamk_f32 v173, v173, 0x3a800000, v210
	v_mul_f32_e32 v201, 0x4b800000, v164
	v_mul_f32_e32 v204, 0x4b800000, v165
	v_mul_f32_e32 v205, 0x4b800000, v166
	v_mul_f32_e32 v225, 0x4b800000, v167
	v_mul_f32_e32 v226, 0x4b800000, v170
	v_mul_f32_e32 v227, 0x4b800000, v171
	v_mul_f32_e32 v228, 0x4b800000, v172
	v_mul_f32_e32 v229, 0x4b800000, v173
	v_cmp_gt_f32_e64 s[62:63], s30, v164
	v_cmp_gt_f32_e64 s[64:65], s30, v165
	v_cmp_gt_f32_e64 s[66:67], s30, v166
	v_cmp_gt_f32_e64 s[68:69], s30, v167
	s_nop 1
	v_cndmask_b32_e64 v164, v164, v201, s[62:63]
	v_cndmask_b32_e64 v165, v165, v204, s[64:65]
	v_cndmask_b32_e64 v166, v166, v205, s[66:67]
	v_cndmask_b32_e64 v167, v167, v225, s[68:69]
	v_rsq_f32_e32 v164, v164
	v_rsq_f32_e32 v165, v165
	v_rsq_f32_e32 v166, v166
	v_rsq_f32_e32 v167, v167
	s_nop 0
	v_mul_f32_e32 v201, 0x45800000, v164
	v_mul_f32_e32 v204, 0x45800000, v165
	v_mul_f32_e32 v205, 0x45800000, v166
	v_mul_f32_e32 v225, 0x45800000, v167
	v_cndmask_b32_e64 v164, v164, v201, s[62:63]
	v_cndmask_b32_e64 v165, v165, v204, s[64:65]
	v_cndmask_b32_e64 v166, v166, v205, s[66:67]
	v_cndmask_b32_e64 v167, v167, v225, s[68:69]
	v_cmp_gt_f32_e64 s[62:63], s30, v170
	v_cmp_gt_f32_e64 s[64:65], s30, v171
	v_cmp_gt_f32_e64 s[66:67], s30, v172
	v_cmp_gt_f32_e64 s[68:69], s30, v173
	s_nop 1
	v_cndmask_b32_e64 v170, v170, v226, s[62:63]
	v_cndmask_b32_e64 v171, v171, v227, s[64:65]
	v_cndmask_b32_e64 v172, v172, v228, s[66:67]
	v_cndmask_b32_e64 v173, v173, v229, s[68:69]
	v_rsq_f32_e32 v170, v170
	v_rsq_f32_e32 v171, v171
	v_rsq_f32_e32 v172, v172
	v_rsq_f32_e32 v173, v173
	s_nop 0
	v_mul_f32_e32 v226, 0x45800000, v170
	v_mul_f32_e32 v227, 0x45800000, v171
	v_mul_f32_e32 v228, 0x45800000, v172
	v_mul_f32_e32 v229, 0x45800000, v173
	v_cndmask_b32_e64 v170, v170, v226, s[62:63]
	v_cndmask_b32_e64 v171, v171, v227, s[64:65]
	v_cndmask_b32_e64 v172, v172, v228, s[66:67]
	v_cndmask_b32_e64 v173, v173, v229, s[68:69]
	s_waitcnt vmcnt(10)
; __device__ __forceinline__ float bf_lo(unsigned w) { return __uint_as_float(w << 16); }
; __device__ __forceinline__ float bf_hi(unsigned w) { return __uint_as_float(w & 0xffff0000u); }
; __device__ __forceinline__ float sigmoidf_(float x) { return 1.0f / (1.0f + __expf(-x)); }
;     __device__ __forceinline__ void operator()(AccT& acc, const Unit& u, int wr, int wc, int fr, int fq) const {
;     ...
;             float* hp = H + (size_t)row * DM + col0; float ss = 0.f; const float rstd = rsqrtf(rs[r & 1] * (1.0f / DM) + 1e-6f);
; #pragma unroll
;             for (int bj = 0; bj < 2; ++bj) { const u32x4 pw = pv[r & 1][bj];
;                 const f32x4 b0 = *(const f32x4*)(bias + col0 + bj * 128), b1 = *(const f32x4*)(bias + col0 + bj * 128 + 4);
;                 const f32x4 p0 = (f32x4){bf_lo(pw.x), bf_hi(pw.x), bf_lo(pw.y), bf_hi(pw.y)}, p1 = (f32x4){bf_lo(pw.z), bf_hi(pw.z), bf_lo(pw.w), bf_hi(pw.w)};
;                 f32x4 g0 = acc[ai][bj][m][0] * rstd + b0, g1 = acc[ai][bj][m][1] * rstd + b1;
; #pragma unroll
;                 for (int j = 0; j < 4; ++j) { g0[j] = sigmoidf_(g0[j]); g1[j] = sigmoidf_(g1[j]); }
	v_pk_fma_f32 v[122:123], v[122:123], v[164:165], v[240:241] op_sel_hi:[1,0,1]
	v_pk_fma_f32 v[124:125], v[124:125], v[164:165], v[242:243] op_sel_hi:[1,0,1]
	v_pk_fma_f32 v[114:115], v[114:115], v[164:165], v[244:245] op_sel_hi:[1,0,1]
	v_pk_fma_f32 v[116:117], v[116:117], v[164:165], v[246:247] op_sel_hi:[1,0,1]
	v_pk_mul_f32 v[122:123], v[122:123], v[206:207]
	v_pk_mul_f32 v[124:125], v[124:125], v[206:207]
	v_pk_mul_f32 v[114:115], v[114:115], v[206:207]
	v_pk_mul_f32 v[116:117], v[116:117], v[206:207]
	v_exp_f32_e32 v122, v122
	v_exp_f32_e32 v123, v123
	v_exp_f32_e32 v124, v124
	v_exp_f32_e32 v125, v125
	v_exp_f32_e32 v114, v114
	v_exp_f32_e32 v115, v115
	v_exp_f32_e32 v116, v116
	v_exp_f32_e32 v117, v117
	v_pk_add_f32 v[122:123], v[122:123], 1.0 op_sel_hi:[1,0]
	v_pk_add_f32 v[124:125], v[124:125], 1.0 op_sel_hi:[1,0]
	v_pk_add_f32 v[114:115], v[114:115], 1.0 op_sel_hi:[1,0]
	v_pk_add_f32 v[116:117], v[116:117], 1.0 op_sel_hi:[1,0]
	v_rcp_f32_e32 v201, v122
	v_rcp_f32_e32 v204, v123
	v_rcp_f32_e32 v205, v124
	v_rcp_f32_e32 v225, v125
	v_rcp_f32_e32 v226, v114
	v_rcp_f32_e32 v227, v115
	v_rcp_f32_e32 v228, v116
	v_rcp_f32_e32 v229, v117
	v_fma_f32 v122, -v122, v201, 1.0
	v_fma_f32 v123, -v123, v204, 1.0
	v_fma_f32 v124, -v124, v205, 1.0
	v_fma_f32 v125, -v125, v225, 1.0
	v_fma_f32 v114, -v114, v226, 1.0
	v_fma_f32 v115, -v115, v227, 1.0
	v_fma_f32 v116, -v116, v228, 1.0
	v_fma_f32 v117, -v117, v229, 1.0
	v_fma_f32 v122, v122, v201, v201
	v_fma_f32 v123, v123, v204, v204
	v_fma_f32 v124, v124, v205, v205
	v_fma_f32 v125, v125, v225, v225
	v_fma_f32 v114, v114, v226, v226
	v_fma_f32 v115, v115, v227, v227
	v_fma_f32 v116, v116, v228, v228
	v_fma_f32 v117, v117, v229, v229
	v_pk_fma_f32 v[110:111], v[110:111], v[164:165], v[248:249] op_sel_hi:[1,0,1]
	v_pk_fma_f32 v[112:113], v[112:113], v[164:165], v[250:251] op_sel_hi:[1,0,1]
	v_pk_fma_f32 v[106:107], v[106:107], v[164:165], v[232:233] op_sel_hi:[1,0,1]
	v_pk_fma_f32 v[108:109], v[108:109], v[164:165], v[234:235] op_sel_hi:[1,0,1]
	v_pk_mul_f32 v[110:111], v[110:111], v[206:207]
	v_pk_mul_f32 v[112:113], v[112:113], v[206:207]
	v_pk_mul_f32 v[106:107], v[106:107], v[206:207]
	v_pk_mul_f32 v[108:109], v[108:109], v[206:207]
	v_exp_f32_e32 v110, v110
	v_exp_f32_e32 v111, v111
	v_exp_f32_e32 v112, v112
	v_exp_f32_e32 v113, v113
	v_exp_f32_e32 v106, v106
	v_exp_f32_e32 v107, v107
	v_exp_f32_e32 v108, v108
	v_exp_f32_e32 v109, v109
	v_pk_add_f32 v[110:111], v[110:111], 1.0 op_sel_hi:[1,0]
	v_pk_add_f32 v[112:113], v[112:113], 1.0 op_sel_hi:[1,0]
	v_pk_add_f32 v[106:107], v[106:107], 1.0 op_sel_hi:[1,0]
	v_pk_add_f32 v[108:109], v[108:109], 1.0 op_sel_hi:[1,0]
	v_rcp_f32_e32 v201, v110
	v_rcp_f32_e32 v204, v111
	v_rcp_f32_e32 v205, v112
	v_rcp_f32_e32 v225, v113
	v_rcp_f32_e32 v226, v106
	v_rcp_f32_e32 v227, v107
	v_rcp_f32_e32 v228, v108
	v_rcp_f32_e32 v229, v109
	v_fma_f32 v110, -v110, v201, 1.0
	v_fma_f32 v111, -v111, v204, 1.0
	v_fma_f32 v112, -v112, v205, 1.0
	v_fma_f32 v113, -v113, v225, 1.0
	v_fma_f32 v106, -v106, v226, 1.0
	v_fma_f32 v107, -v107, v227, 1.0
	v_fma_f32 v108, -v108, v228, 1.0
	v_fma_f32 v109, -v109, v229, 1.0
	v_fma_f32 v110, v110, v201, v201
	v_fma_f32 v111, v111, v204, v204
	v_fma_f32 v112, v112, v205, v205
	v_fma_f32 v113, v113, v225, v225
	v_fma_f32 v106, v106, v226, v226
	v_fma_f32 v107, v107, v227, v227
	v_fma_f32 v108, v108, v228, v228
	v_fma_f32 v109, v109, v229, v229
	v_pk_fma_f32 v[126:127], v[126:127], v[164:165], v[240:241] op_sel:[0,1,0] op_sel_hi:[1,1,1]
	v_pk_fma_f32 v[128:129], v[128:129], v[164:165], v[242:243] op_sel:[0,1,0] op_sel_hi:[1,1,1]
	v_pk_fma_f32 v[118:119], v[118:119], v[164:165], v[244:245] op_sel:[0,1,0] op_sel_hi:[1,1,1]
	v_pk_fma_f32 v[120:121], v[120:121], v[164:165], v[246:247] op_sel:[0,1,0] op_sel_hi:[1,1,1]
	v_pk_mul_f32 v[126:127], v[126:127], v[206:207]
	v_pk_mul_f32 v[128:129], v[128:129], v[206:207]
	v_pk_mul_f32 v[118:119], v[118:119], v[206:207]
	v_pk_mul_f32 v[120:121], v[120:121], v[206:207]
	v_exp_f32_e32 v126, v126
	v_exp_f32_e32 v127, v127
	v_exp_f32_e32 v128, v128
	v_exp_f32_e32 v129, v129
	v_exp_f32_e32 v118, v118
	v_exp_f32_e32 v119, v119
	v_exp_f32_e32 v120, v120
	v_exp_f32_e32 v121, v121
	v_pk_add_f32 v[126:127], v[126:127], 1.0 op_sel_hi:[1,0]
	v_pk_add_f32 v[128:129], v[128:129], 1.0 op_sel_hi:[1,0]
	v_pk_add_f32 v[118:119], v[118:119], 1.0 op_sel_hi:[1,0]
	v_pk_add_f32 v[120:121], v[120:121], 1.0 op_sel_hi:[1,0]
	v_rcp_f32_e32 v201, v126
	v_rcp_f32_e32 v204, v127
	v_rcp_f32_e32 v205, v128
	v_rcp_f32_e32 v225, v129
	v_rcp_f32_e32 v226, v118
	v_rcp_f32_e32 v227, v119
	v_rcp_f32_e32 v228, v120
	v_rcp_f32_e32 v229, v121
	v_fma_f32 v126, -v126, v201, 1.0
	v_fma_f32 v127, -v127, v204, 1.0
	v_fma_f32 v128, -v128, v205, 1.0
	v_fma_f32 v129, -v129, v225, 1.0
	v_fma_f32 v118, -v118, v226, 1.0
	v_fma_f32 v119, -v119, v227, 1.0
	v_fma_f32 v120, -v120, v228, 1.0
	v_fma_f32 v121, -v121, v229, 1.0
	v_fma_f32 v126, v126, v201, v201
	v_fma_f32 v127, v127, v204, v204
	v_fma_f32 v128, v128, v205, v205
	v_fma_f32 v129, v129, v225, v225
	v_fma_f32 v118, v118, v226, v226
	v_fma_f32 v119, v119, v227, v227
	v_fma_f32 v120, v120, v228, v228
	v_fma_f32 v121, v121, v229, v229
	v_pk_fma_f32 v[102:103], v[102:103], v[164:165], v[248:249] op_sel:[0,1,0] op_sel_hi:[1,1,1]
	v_pk_fma_f32 v[104:105], v[104:105], v[164:165], v[250:251] op_sel:[0,1,0] op_sel_hi:[1,1,1]
	v_pk_fma_f32 v[98:99], v[98:99], v[164:165], v[232:233] op_sel:[0,1,0] op_sel_hi:[1,1,1]
	v_pk_fma_f32 v[100:101], v[100:101], v[164:165], v[234:235] op_sel:[0,1,0] op_sel_hi:[1,1,1]
	v_pk_mul_f32 v[102:103], v[102:103], v[206:207]
	v_pk_mul_f32 v[104:105], v[104:105], v[206:207]
; __device__ __forceinline__ float bf_lo(unsigned w) { return __uint_as_float(w << 16); }
; __device__ __forceinline__ float bf_hi(unsigned w) { return __uint_as_float(w & 0xffff0000u); }
; __device__ __forceinline__ float sigmoidf_(float x) { return 1.0f / (1.0f + __expf(-x)); }
;     __device__ __forceinline__ void operator()(AccT& acc, const Unit& u, int wr, int wc, int fr, int fq) const {
;     ...
;             float* hp = H + (size_t)row * DM + col0; float ss = 0.f; const float rstd = rsqrtf(rs[r & 1] * (1.0f / DM) + 1e-6f);
; #pragma unroll
;             for (int bj = 0; bj < 2; ++bj) { const u32x4 pw = pv[r & 1][bj];
;                 const f32x4 b0 = *(const f32x4*)(bias + col0 + bj * 128), b1 = *(const f32x4*)(bias + col0 + bj * 128 + 4);
;                 const f32x4 p0 = (f32x4){bf_lo(pw.x), bf_hi(pw.x), bf_lo(pw.y), bf_hi(pw.y)}, p1 = (f32x4){bf_lo(pw.z), bf_hi(pw.z), bf_lo(pw.w), bf_hi(pw.w)};
;                 f32x4 g0 = acc[ai][bj][m][0] * rstd + b0, g1 = acc[ai][bj][m][1] * rstd + b1;
; #pragma unroll
;                 for (int j = 0; j < 4; ++j) { g0[j] = sigmoidf_(g0[j]); g1[j] = sigmoidf_(g1[j]); }
	v_pk_mul_f32 v[98:99], v[98:99], v[206:207]
	v_pk_mul_f32 v[100:101], v[100:101], v[206:207]
	v_exp_f32_e32 v102, v102
	v_exp_f32_e32 v103, v103
	v_exp_f32_e32 v104, v104
	v_exp_f32_e32 v105, v105
	v_exp_f32_e32 v98, v98
	v_exp_f32_e32 v99, v99
	v_exp_f32_e32 v100, v100
	v_exp_f32_e32 v101, v101
	v_pk_add_f32 v[102:103], v[102:103], 1.0 op_sel_hi:[1,0]
	v_pk_add_f32 v[104:105], v[104:105], 1.0 op_sel_hi:[1,0]
	v_pk_add_f32 v[98:99], v[98:99], 1.0 op_sel_hi:[1,0]
	v_pk_add_f32 v[100:101], v[100:101], 1.0 op_sel_hi:[1,0]
	v_rcp_f32_e32 v201, v102
	v_rcp_f32_e32 v204, v103
	v_rcp_f32_e32 v205, v104
	v_rcp_f32_e32 v225, v105
	v_rcp_f32_e32 v226, v98
	v_rcp_f32_e32 v227, v99
	v_rcp_f32_e32 v228, v100
	v_rcp_f32_e32 v229, v101
	v_fma_f32 v102, -v102, v201, 1.0
	v_fma_f32 v103, -v103, v204, 1.0
	v_fma_f32 v104, -v104, v205, 1.0
	v_fma_f32 v105, -v105, v225, 1.0
	v_fma_f32 v98, -v98, v226, 1.0
	v_fma_f32 v99, -v99, v227, 1.0
	v_fma_f32 v100, -v100, v228, 1.0
	v_fma_f32 v101, -v101, v229, 1.0
	v_fma_f32 v102, v102, v201, v201
	v_fma_f32 v103, v103, v204, v204
	v_fma_f32 v104, v104, v205, v205
	v_fma_f32 v105, v105, v225, v225
	v_fma_f32 v98, v98, v226, v226
	v_fma_f32 v99, v99, v227, v227
	v_fma_f32 v100, v100, v228, v228
	v_fma_f32 v101, v101, v229, v229
	v_pk_fma_f32 v[94:95], v[94:95], v[166:167], v[240:241] op_sel_hi:[1,0,1]
	v_pk_fma_f32 v[96:97], v[96:97], v[166:167], v[242:243] op_sel_hi:[1,0,1]
	v_pk_fma_f32 v[90:91], v[90:91], v[166:167], v[244:245] op_sel_hi:[1,0,1]
	v_pk_fma_f32 v[92:93], v[92:93], v[166:167], v[246:247] op_sel_hi:[1,0,1]
	v_pk_mul_f32 v[94:95], v[94:95], v[206:207]
	v_pk_mul_f32 v[96:97], v[96:97], v[206:207]
	v_pk_mul_f32 v[90:91], v[90:91], v[206:207]
	v_pk_mul_f32 v[92:93], v[92:93], v[206:207]
	v_exp_f32_e32 v94, v94
	v_exp_f32_e32 v95, v95
	v_exp_f32_e32 v96, v96
	v_exp_f32_e32 v97, v97
	v_exp_f32_e32 v90, v90
	v_exp_f32_e32 v91, v91
	v_exp_f32_e32 v92, v92
	v_exp_f32_e32 v93, v93
	v_pk_add_f32 v[94:95], v[94:95], 1.0 op_sel_hi:[1,0]
	v_pk_add_f32 v[96:97], v[96:97], 1.0 op_sel_hi:[1,0]
	v_pk_add_f32 v[90:91], v[90:91], 1.0 op_sel_hi:[1,0]
	v_pk_add_f32 v[92:93], v[92:93], 1.0 op_sel_hi:[1,0]
	v_rcp_f32_e32 v201, v94
	v_rcp_f32_e32 v204, v95
	v_rcp_f32_e32 v205, v96
	v_rcp_f32_e32 v225, v97
	v_rcp_f32_e32 v226, v90
	v_rcp_f32_e32 v227, v91
	v_rcp_f32_e32 v228, v92
	v_rcp_f32_e32 v229, v93
	v_fma_f32 v94, -v94, v201, 1.0
	v_fma_f32 v95, -v95, v204, 1.0
	v_fma_f32 v96, -v96, v205, 1.0
	v_fma_f32 v97, -v97, v225, 1.0
	v_fma_f32 v90, -v90, v226, 1.0
	v_fma_f32 v91, -v91, v227, 1.0
	v_fma_f32 v92, -v92, v228, 1.0
	v_fma_f32 v93, -v93, v229, 1.0
	v_fma_f32 v94, v94, v201, v201
	v_fma_f32 v95, v95, v204, v204
	v_fma_f32 v96, v96, v205, v205
	v_fma_f32 v97, v97, v225, v225
	v_fma_f32 v90, v90, v226, v226
	v_fma_f32 v91, v91, v227, v227
	v_fma_f32 v92, v92, v228, v228
	v_fma_f32 v93, v93, v229, v229
	v_pk_fma_f32 v[86:87], v[86:87], v[166:167], v[248:249] op_sel_hi:[1,0,1]
	v_pk_fma_f32 v[88:89], v[88:89], v[166:167], v[250:251] op_sel_hi:[1,0,1]
	v_pk_fma_f32 v[82:83], v[82:83], v[166:167], v[232:233] op_sel_hi:[1,0,1]
	v_pk_fma_f32 v[84:85], v[84:85], v[166:167], v[234:235] op_sel_hi:[1,0,1]
	v_pk_mul_f32 v[86:87], v[86:87], v[206:207]
	v_pk_mul_f32 v[88:89], v[88:89], v[206:207]
	v_pk_mul_f32 v[82:83], v[82:83], v[206:207]
	v_pk_mul_f32 v[84:85], v[84:85], v[206:207]
	v_exp_f32_e32 v86, v86
	v_exp_f32_e32 v87, v87
	v_exp_f32_e32 v88, v88
	v_exp_f32_e32 v89, v89
	v_exp_f32_e32 v82, v82
	v_exp_f32_e32 v83, v83
	v_exp_f32_e32 v84, v84
	v_exp_f32_e32 v85, v85
	v_pk_add_f32 v[86:87], v[86:87], 1.0 op_sel_hi:[1,0]
	v_pk_add_f32 v[88:89], v[88:89], 1.0 op_sel_hi:[1,0]
	v_pk_add_f32 v[82:83], v[82:83], 1.0 op_sel_hi:[1,0]
	v_pk_add_f32 v[84:85], v[84:85], 1.0 op_sel_hi:[1,0]
	v_rcp_f32_e32 v201, v86
	v_rcp_f32_e32 v204, v87
	v_rcp_f32_e32 v205, v88
	v_rcp_f32_e32 v225, v89
	v_rcp_f32_e32 v226, v82
	v_rcp_f32_e32 v227, v83
	v_rcp_f32_e32 v228, v84
	v_rcp_f32_e32 v229, v85
	v_fma_f32 v86, -v86, v201, 1.0
	v_fma_f32 v87, -v87, v204, 1.0
	v_fma_f32 v88, -v88, v205, 1.0
	v_fma_f32 v89, -v89, v225, 1.0
	v_fma_f32 v82, -v82, v226, 1.0
	v_fma_f32 v83, -v83, v227, 1.0
	v_fma_f32 v84, -v84, v228, 1.0
	v_fma_f32 v85, -v85, v229, 1.0
	v_fma_f32 v86, v86, v201, v201
	v_fma_f32 v87, v87, v204, v204
	v_fma_f32 v88, v88, v205, v205
	v_fma_f32 v89, v89, v225, v225
	v_fma_f32 v82, v82, v226, v226
	v_fma_f32 v83, v83, v227, v227
	v_fma_f32 v84, v84, v228, v228
	v_fma_f32 v85, v85, v229, v229
	v_pk_fma_f32 v[78:79], v[78:79], v[166:167], v[240:241] op_sel:[0,1,0] op_sel_hi:[1,1,1]
	v_pk_fma_f32 v[80:81], v[80:81], v[166:167], v[242:243] op_sel:[0,1,0] op_sel_hi:[1,1,1]
	v_pk_fma_f32 v[74:75], v[74:75], v[166:167], v[244:245] op_sel:[0,1,0] op_sel_hi:[1,1,1]
	v_pk_fma_f32 v[76:77], v[76:77], v[166:167], v[246:247] op_sel:[0,1,0] op_sel_hi:[1,1,1]
	v_pk_mul_f32 v[78:79], v[78:79], v[206:207]
	v_pk_mul_f32 v[80:81], v[80:81], v[206:207]
	v_pk_mul_f32 v[74:75], v[74:75], v[206:207]
	v_pk_mul_f32 v[76:77], v[76:77], v[206:207]
	v_exp_f32_e32 v78, v78
	v_exp_f32_e32 v79, v79
	v_exp_f32_e32 v80, v80
	v_exp_f32_e32 v81, v81
	v_exp_f32_e32 v74, v74
	v_exp_f32_e32 v75, v75
	v_exp_f32_e32 v76, v76
	v_exp_f32_e32 v77, v77
	v_pk_add_f32 v[78:79], v[78:79], 1.0 op_sel_hi:[1,0]
	v_pk_add_f32 v[80:81], v[80:81], 1.0 op_sel_hi:[1,0]
	v_pk_add_f32 v[74:75], v[74:75], 1.0 op_sel_hi:[1,0]
	v_pk_add_f32 v[76:77], v[76:77], 1.0 op_sel_hi:[1,0]
	v_rcp_f32_e32 v201, v78
	v_rcp_f32_e32 v204, v79
	v_rcp_f32_e32 v205, v80
	v_rcp_f32_e32 v225, v81
	v_rcp_f32_e32 v226, v74
	v_rcp_f32_e32 v227, v75
	v_rcp_f32_e32 v228, v76
	v_rcp_f32_e32 v229, v77
	v_fma_f32 v78, -v78, v201, 1.0
; __device__ __forceinline__ float bf_lo(unsigned w) { return __uint_as_float(w << 16); }
; __device__ __forceinline__ float bf_hi(unsigned w) { return __uint_as_float(w & 0xffff0000u); }
; __device__ __forceinline__ float sigmoidf_(float x) { return 1.0f / (1.0f + __expf(-x)); }
;     __device__ __forceinline__ void operator()(AccT& acc, const Unit& u, int wr, int wc, int fr, int fq) const {
;     ...
;             float* hp = H + (size_t)row * DM + col0; float ss = 0.f; const float rstd = rsqrtf(rs[r & 1] * (1.0f / DM) + 1e-6f);
; #pragma unroll
;             for (int bj = 0; bj < 2; ++bj) { const u32x4 pw = pv[r & 1][bj];
;                 const f32x4 b0 = *(const f32x4*)(bias + col0 + bj * 128), b1 = *(const f32x4*)(bias + col0 + bj * 128 + 4);
;                 const f32x4 p0 = (f32x4){bf_lo(pw.x), bf_hi(pw.x), bf_lo(pw.y), bf_hi(pw.y)}, p1 = (f32x4){bf_lo(pw.z), bf_hi(pw.z), bf_lo(pw.w), bf_hi(pw.w)};
;                 f32x4 g0 = acc[ai][bj][m][0] * rstd + b0, g1 = acc[ai][bj][m][1] * rstd + b1;
; #pragma unroll
;                 for (int j = 0; j < 4; ++j) { g0[j] = sigmoidf_(g0[j]); g1[j] = sigmoidf_(g1[j]); }
	v_fma_f32 v79, -v79, v204, 1.0
	v_fma_f32 v80, -v80, v205, 1.0
	v_fma_f32 v81, -v81, v225, 1.0
	v_fma_f32 v74, -v74, v226, 1.0
	v_fma_f32 v75, -v75, v227, 1.0
	v_fma_f32 v76, -v76, v228, 1.0
	v_fma_f32 v77, -v77, v229, 1.0
	v_fma_f32 v78, v78, v201, v201
	v_fma_f32 v79, v79, v204, v204
	v_fma_f32 v80, v80, v205, v205
	v_fma_f32 v81, v81, v225, v225
	v_fma_f32 v74, v74, v226, v226
	v_fma_f32 v75, v75, v227, v227
	v_fma_f32 v76, v76, v228, v228
	v_fma_f32 v77, v77, v229, v229
	v_pk_fma_f32 v[70:71], v[70:71], v[166:167], v[248:249] op_sel:[0,1,0] op_sel_hi:[1,1,1]
	v_pk_fma_f32 v[72:73], v[72:73], v[166:167], v[250:251] op_sel:[0,1,0] op_sel_hi:[1,1,1]
	v_pk_fma_f32 v[66:67], v[66:67], v[166:167], v[232:233] op_sel:[0,1,0] op_sel_hi:[1,1,1]
	v_pk_fma_f32 v[68:69], v[68:69], v[166:167], v[234:235] op_sel:[0,1,0] op_sel_hi:[1,1,1]
	v_pk_mul_f32 v[70:71], v[70:71], v[206:207]
	v_pk_mul_f32 v[72:73], v[72:73], v[206:207]
	v_pk_mul_f32 v[66:67], v[66:67], v[206:207]
	v_pk_mul_f32 v[68:69], v[68:69], v[206:207]
	v_exp_f32_e32 v70, v70
	v_exp_f32_e32 v71, v71
	v_exp_f32_e32 v72, v72
	v_exp_f32_e32 v73, v73
	v_exp_f32_e32 v66, v66
	v_exp_f32_e32 v67, v67
	v_exp_f32_e32 v68, v68
	v_exp_f32_e32 v69, v69
	v_pk_add_f32 v[70:71], v[70:71], 1.0 op_sel_hi:[1,0]
	v_pk_add_f32 v[72:73], v[72:73], 1.0 op_sel_hi:[1,0]
	v_pk_add_f32 v[66:67], v[66:67], 1.0 op_sel_hi:[1,0]
	v_pk_add_f32 v[68:69], v[68:69], 1.0 op_sel_hi:[1,0]
	v_rcp_f32_e32 v201, v70
	v_rcp_f32_e32 v204, v71
	v_rcp_f32_e32 v205, v72
	v_rcp_f32_e32 v225, v73
	v_rcp_f32_e32 v226, v66
	v_rcp_f32_e32 v227, v67
	v_rcp_f32_e32 v228, v68
	v_rcp_f32_e32 v229, v69
	v_fma_f32 v70, -v70, v201, 1.0
	v_fma_f32 v71, -v71, v204, 1.0
	v_fma_f32 v72, -v72, v205, 1.0
	v_fma_f32 v73, -v73, v225, 1.0
	v_fma_f32 v66, -v66, v226, 1.0
	v_fma_f32 v67, -v67, v227, 1.0
	v_fma_f32 v68, -v68, v228, 1.0
	v_fma_f32 v69, -v69, v229, 1.0
	v_fma_f32 v70, v70, v201, v201
	v_fma_f32 v71, v71, v204, v204
	v_fma_f32 v72, v72, v205, v205
	v_fma_f32 v73, v73, v225, v225
	v_fma_f32 v66, v66, v226, v226
	v_fma_f32 v67, v67, v227, v227
	v_fma_f32 v68, v68, v228, v228
	v_fma_f32 v69, v69, v229, v229
	v_pk_fma_f32 v[62:63], v[62:63], v[170:171], v[240:241] op_sel_hi:[1,0,1]
	v_pk_fma_f32 v[64:65], v[64:65], v[170:171], v[242:243] op_sel_hi:[1,0,1]
	v_pk_fma_f32 v[58:59], v[58:59], v[170:171], v[244:245] op_sel_hi:[1,0,1]
	v_pk_fma_f32 v[60:61], v[60:61], v[170:171], v[246:247] op_sel_hi:[1,0,1]
	v_pk_mul_f32 v[62:63], v[62:63], v[206:207]
	v_pk_mul_f32 v[64:65], v[64:65], v[206:207]
	v_pk_mul_f32 v[58:59], v[58:59], v[206:207]
	v_pk_mul_f32 v[60:61], v[60:61], v[206:207]
	v_exp_f32_e32 v62, v62
	v_exp_f32_e32 v63, v63
	v_exp_f32_e32 v64, v64
	v_exp_f32_e32 v65, v65
	v_exp_f32_e32 v58, v58
	v_exp_f32_e32 v59, v59
	v_exp_f32_e32 v60, v60
	v_exp_f32_e32 v61, v61
	v_pk_add_f32 v[62:63], v[62:63], 1.0 op_sel_hi:[1,0]
	v_pk_add_f32 v[64:65], v[64:65], 1.0 op_sel_hi:[1,0]
	v_pk_add_f32 v[58:59], v[58:59], 1.0 op_sel_hi:[1,0]
	v_pk_add_f32 v[60:61], v[60:61], 1.0 op_sel_hi:[1,0]
	v_rcp_f32_e32 v201, v62
	v_rcp_f32_e32 v204, v63
	v_rcp_f32_e32 v205, v64
	v_rcp_f32_e32 v225, v65
	v_rcp_f32_e32 v226, v58
	v_rcp_f32_e32 v227, v59
	v_rcp_f32_e32 v228, v60
	v_rcp_f32_e32 v229, v61
	v_fma_f32 v62, -v62, v201, 1.0
	v_fma_f32 v63, -v63, v204, 1.0
	v_fma_f32 v64, -v64, v205, 1.0
	v_fma_f32 v65, -v65, v225, 1.0
	v_fma_f32 v58, -v58, v226, 1.0
	v_fma_f32 v59, -v59, v227, 1.0
	v_fma_f32 v60, -v60, v228, 1.0
	v_fma_f32 v61, -v61, v229, 1.0
	v_fma_f32 v62, v62, v201, v201
	v_fma_f32 v63, v63, v204, v204
	v_fma_f32 v64, v64, v205, v205
	v_fma_f32 v65, v65, v225, v225
	v_fma_f32 v58, v58, v226, v226
	v_fma_f32 v59, v59, v227, v227
	v_fma_f32 v60, v60, v228, v228
	v_fma_f32 v61, v61, v229, v229
	v_pk_fma_f32 v[54:55], v[54:55], v[170:171], v[248:249] op_sel_hi:[1,0,1]
	v_pk_fma_f32 v[56:57], v[56:57], v[170:171], v[250:251] op_sel_hi:[1,0,1]
	v_pk_fma_f32 v[50:51], v[50:51], v[170:171], v[232:233] op_sel_hi:[1,0,1]
	v_pk_fma_f32 v[52:53], v[52:53], v[170:171], v[234:235] op_sel_hi:[1,0,1]
	v_pk_mul_f32 v[54:55], v[54:55], v[206:207]
	v_pk_mul_f32 v[56:57], v[56:57], v[206:207]
	v_pk_mul_f32 v[50:51], v[50:51], v[206:207]
	v_pk_mul_f32 v[52:53], v[52:53], v[206:207]
	v_exp_f32_e32 v54, v54
	v_exp_f32_e32 v55, v55
	v_exp_f32_e32 v56, v56
	v_exp_f32_e32 v57, v57
	v_exp_f32_e32 v50, v50
	v_exp_f32_e32 v51, v51
	v_exp_f32_e32 v52, v52
	v_exp_f32_e32 v53, v53
	v_pk_add_f32 v[54:55], v[54:55], 1.0 op_sel_hi:[1,0]
	v_pk_add_f32 v[56:57], v[56:57], 1.0 op_sel_hi:[1,0]
	v_pk_add_f32 v[50:51], v[50:51], 1.0 op_sel_hi:[1,0]
	v_pk_add_f32 v[52:53], v[52:53], 1.0 op_sel_hi:[1,0]
	v_rcp_f32_e32 v201, v54
	v_rcp_f32_e32 v204, v55
	v_rcp_f32_e32 v205, v56
	v_rcp_f32_e32 v225, v57
	v_rcp_f32_e32 v226, v50
	v_rcp_f32_e32 v227, v51
	v_rcp_f32_e32 v228, v52
	v_rcp_f32_e32 v229, v53
	v_fma_f32 v54, -v54, v201, 1.0
	v_fma_f32 v55, -v55, v204, 1.0
	v_fma_f32 v56, -v56, v205, 1.0
	v_fma_f32 v57, -v57, v225, 1.0
	v_fma_f32 v50, -v50, v226, 1.0
	v_fma_f32 v51, -v51, v227, 1.0
	v_fma_f32 v52, -v52, v228, 1.0
	v_fma_f32 v53, -v53, v229, 1.0
	v_fma_f32 v54, v54, v201, v201
	v_fma_f32 v55, v55, v204, v204
	v_fma_f32 v56, v56, v205, v205
	v_fma_f32 v57, v57, v225, v225
	v_fma_f32 v50, v50, v226, v226
	v_fma_f32 v51, v51, v227, v227
	v_fma_f32 v52, v52, v228, v228
	v_fma_f32 v53, v53, v229, v229
	v_pk_fma_f32 v[46:47], v[46:47], v[170:171], v[240:241] op_sel:[0,1,0] op_sel_hi:[1,1,1]
	v_pk_fma_f32 v[48:49], v[48:49], v[170:171], v[242:243] op_sel:[0,1,0] op_sel_hi:[1,1,1]
	v_pk_fma_f32 v[42:43], v[42:43], v[170:171], v[244:245] op_sel:[0,1,0] op_sel_hi:[1,1,1]
; __device__ __forceinline__ float bf_lo(unsigned w) { return __uint_as_float(w << 16); }
; __device__ __forceinline__ float bf_hi(unsigned w) { return __uint_as_float(w & 0xffff0000u); }
; __device__ __forceinline__ float sigmoidf_(float x) { return 1.0f / (1.0f + __expf(-x)); }
;     __device__ __forceinline__ void operator()(AccT& acc, const Unit& u, int wr, int wc, int fr, int fq) const {
;     ...
;             float* hp = H + (size_t)row * DM + col0; float ss = 0.f; const float rstd = rsqrtf(rs[r & 1] * (1.0f / DM) + 1e-6f);
; #pragma unroll
;             for (int bj = 0; bj < 2; ++bj) { const u32x4 pw = pv[r & 1][bj];
;                 const f32x4 b0 = *(const f32x4*)(bias + col0 + bj * 128), b1 = *(const f32x4*)(bias + col0 + bj * 128 + 4);
;                 const f32x4 p0 = (f32x4){bf_lo(pw.x), bf_hi(pw.x), bf_lo(pw.y), bf_hi(pw.y)}, p1 = (f32x4){bf_lo(pw.z), bf_hi(pw.z), bf_lo(pw.w), bf_hi(pw.w)};
;                 f32x4 g0 = acc[ai][bj][m][0] * rstd + b0, g1 = acc[ai][bj][m][1] * rstd + b1;
; #pragma unroll
;                 for (int j = 0; j < 4; ++j) { g0[j] = sigmoidf_(g0[j]); g1[j] = sigmoidf_(g1[j]); }
	v_pk_fma_f32 v[44:45], v[44:45], v[170:171], v[246:247] op_sel:[0,1,0] op_sel_hi:[1,1,1]
	v_pk_mul_f32 v[46:47], v[46:47], v[206:207]
	v_pk_mul_f32 v[48:49], v[48:49], v[206:207]
	v_pk_mul_f32 v[42:43], v[42:43], v[206:207]
	v_pk_mul_f32 v[44:45], v[44:45], v[206:207]
	v_exp_f32_e32 v46, v46
	v_exp_f32_e32 v47, v47
	v_exp_f32_e32 v48, v48
	v_exp_f32_e32 v49, v49
	v_exp_f32_e32 v42, v42
	v_exp_f32_e32 v43, v43
	v_exp_f32_e32 v44, v44
	v_exp_f32_e32 v45, v45
	v_pk_add_f32 v[46:47], v[46:47], 1.0 op_sel_hi:[1,0]
	v_pk_add_f32 v[48:49], v[48:49], 1.0 op_sel_hi:[1,0]
	v_pk_add_f32 v[42:43], v[42:43], 1.0 op_sel_hi:[1,0]
	v_pk_add_f32 v[44:45], v[44:45], 1.0 op_sel_hi:[1,0]
	v_rcp_f32_e32 v201, v46
	v_rcp_f32_e32 v204, v47
	v_rcp_f32_e32 v205, v48
	v_rcp_f32_e32 v225, v49
	v_rcp_f32_e32 v226, v42
	v_rcp_f32_e32 v227, v43
	v_rcp_f32_e32 v228, v44
	v_rcp_f32_e32 v229, v45
	v_fma_f32 v46, -v46, v201, 1.0
	v_fma_f32 v47, -v47, v204, 1.0
	v_fma_f32 v48, -v48, v205, 1.0
	v_fma_f32 v49, -v49, v225, 1.0
	v_fma_f32 v42, -v42, v226, 1.0
	v_fma_f32 v43, -v43, v227, 1.0
	v_fma_f32 v44, -v44, v228, 1.0
	v_fma_f32 v45, -v45, v229, 1.0
	v_fma_f32 v46, v46, v201, v201
	v_fma_f32 v47, v47, v204, v204
	v_fma_f32 v48, v48, v205, v205
	v_fma_f32 v49, v49, v225, v225
	v_fma_f32 v42, v42, v226, v226
	v_fma_f32 v43, v43, v227, v227
	v_fma_f32 v44, v44, v228, v228
	v_fma_f32 v45, v45, v229, v229
	v_pk_fma_f32 v[38:39], v[38:39], v[170:171], v[248:249] op_sel:[0,1,0] op_sel_hi:[1,1,1]
	v_pk_fma_f32 v[40:41], v[40:41], v[170:171], v[250:251] op_sel:[0,1,0] op_sel_hi:[1,1,1]
	v_pk_fma_f32 v[34:35], v[34:35], v[170:171], v[232:233] op_sel:[0,1,0] op_sel_hi:[1,1,1]
	v_pk_fma_f32 v[36:37], v[36:37], v[170:171], v[234:235] op_sel:[0,1,0] op_sel_hi:[1,1,1]
	v_pk_mul_f32 v[38:39], v[38:39], v[206:207]
	v_pk_mul_f32 v[40:41], v[40:41], v[206:207]
	v_pk_mul_f32 v[34:35], v[34:35], v[206:207]
	v_pk_mul_f32 v[36:37], v[36:37], v[206:207]
	v_exp_f32_e32 v38, v38
	v_exp_f32_e32 v39, v39
	v_exp_f32_e32 v40, v40
	v_exp_f32_e32 v41, v41
	v_exp_f32_e32 v34, v34
	v_exp_f32_e32 v35, v35
	v_exp_f32_e32 v36, v36
	v_exp_f32_e32 v37, v37
	v_pk_add_f32 v[38:39], v[38:39], 1.0 op_sel_hi:[1,0]
	v_pk_add_f32 v[40:41], v[40:41], 1.0 op_sel_hi:[1,0]
	v_pk_add_f32 v[34:35], v[34:35], 1.0 op_sel_hi:[1,0]
	v_pk_add_f32 v[36:37], v[36:37], 1.0 op_sel_hi:[1,0]
	v_rcp_f32_e32 v201, v38
	v_rcp_f32_e32 v204, v39
	v_rcp_f32_e32 v205, v40
	v_rcp_f32_e32 v225, v41
	v_rcp_f32_e32 v226, v34
	v_rcp_f32_e32 v227, v35
	v_rcp_f32_e32 v228, v36
	v_rcp_f32_e32 v229, v37
	v_fma_f32 v38, -v38, v201, 1.0
	v_fma_f32 v39, -v39, v204, 1.0
	v_fma_f32 v40, -v40, v205, 1.0
	v_fma_f32 v41, -v41, v225, 1.0
	v_fma_f32 v34, -v34, v226, 1.0
	v_fma_f32 v35, -v35, v227, 1.0
	v_fma_f32 v36, -v36, v228, 1.0
	v_fma_f32 v37, -v37, v229, 1.0
	v_fma_f32 v38, v38, v201, v201
	v_fma_f32 v39, v39, v204, v204
	v_fma_f32 v40, v40, v205, v205
	v_fma_f32 v41, v41, v225, v225
	v_fma_f32 v34, v34, v226, v226
	v_fma_f32 v35, v35, v227, v227
	v_fma_f32 v36, v36, v228, v228
	v_fma_f32 v37, v37, v229, v229
	v_pk_fma_f32 v[30:31], v[30:31], v[172:173], v[240:241] op_sel_hi:[1,0,1]
	v_pk_fma_f32 v[32:33], v[32:33], v[172:173], v[242:243] op_sel_hi:[1,0,1]
	v_pk_fma_f32 v[26:27], v[26:27], v[172:173], v[244:245] op_sel_hi:[1,0,1]
	v_pk_fma_f32 v[28:29], v[28:29], v[172:173], v[246:247] op_sel_hi:[1,0,1]
	v_pk_mul_f32 v[30:31], v[30:31], v[206:207]
	v_pk_mul_f32 v[32:33], v[32:33], v[206:207]
	v_pk_mul_f32 v[26:27], v[26:27], v[206:207]
	v_pk_mul_f32 v[28:29], v[28:29], v[206:207]
	v_exp_f32_e32 v30, v30
	v_exp_f32_e32 v31, v31
	v_exp_f32_e32 v32, v32
	v_exp_f32_e32 v33, v33
	v_exp_f32_e32 v26, v26
	v_exp_f32_e32 v27, v27
	v_exp_f32_e32 v28, v28
	v_exp_f32_e32 v29, v29
	v_pk_add_f32 v[30:31], v[30:31], 1.0 op_sel_hi:[1,0]
	v_pk_add_f32 v[32:33], v[32:33], 1.0 op_sel_hi:[1,0]
	v_pk_add_f32 v[26:27], v[26:27], 1.0 op_sel_hi:[1,0]
	v_pk_add_f32 v[28:29], v[28:29], 1.0 op_sel_hi:[1,0]
	v_rcp_f32_e32 v201, v30
	v_rcp_f32_e32 v204, v31
	v_rcp_f32_e32 v205, v32
	v_rcp_f32_e32 v225, v33
	v_rcp_f32_e32 v226, v26
	v_rcp_f32_e32 v227, v27
	v_rcp_f32_e32 v228, v28
	v_rcp_f32_e32 v229, v29
	v_fma_f32 v30, -v30, v201, 1.0
	v_fma_f32 v31, -v31, v204, 1.0
	v_fma_f32 v32, -v32, v205, 1.0
	v_fma_f32 v33, -v33, v225, 1.0
	v_fma_f32 v26, -v26, v226, 1.0
	v_fma_f32 v27, -v27, v227, 1.0
	v_fma_f32 v28, -v28, v228, 1.0
	v_fma_f32 v29, -v29, v229, 1.0
	v_fma_f32 v30, v30, v201, v201
	v_fma_f32 v31, v31, v204, v204
	v_fma_f32 v32, v32, v205, v205
	v_fma_f32 v33, v33, v225, v225
	v_fma_f32 v26, v26, v226, v226
	v_fma_f32 v27, v27, v227, v227
	v_fma_f32 v28, v28, v228, v228
	v_fma_f32 v29, v29, v229, v229
	v_pk_fma_f32 v[22:23], v[22:23], v[172:173], v[248:249] op_sel_hi:[1,0,1]
	v_pk_fma_f32 v[24:25], v[24:25], v[172:173], v[250:251] op_sel_hi:[1,0,1]
	v_pk_fma_f32 v[18:19], v[18:19], v[172:173], v[232:233] op_sel_hi:[1,0,1]
	v_pk_fma_f32 v[20:21], v[20:21], v[172:173], v[234:235] op_sel_hi:[1,0,1]
	v_pk_mul_f32 v[22:23], v[22:23], v[206:207]
	v_pk_mul_f32 v[24:25], v[24:25], v[206:207]
	v_pk_mul_f32 v[18:19], v[18:19], v[206:207]
	v_pk_mul_f32 v[20:21], v[20:21], v[206:207]
	v_exp_f32_e32 v22, v22
	v_exp_f32_e32 v23, v23
	v_exp_f32_e32 v24, v24
	v_exp_f32_e32 v25, v25
	v_exp_f32_e32 v18, v18
	v_exp_f32_e32 v19, v19
	v_exp_f32_e32 v20, v20
	v_exp_f32_e32 v21, v21
	v_pk_add_f32 v[22:23], v[22:23], 1.0 op_sel_hi:[1,0]
	v_pk_add_f32 v[24:25], v[24:25], 1.0 op_sel_hi:[1,0]
	v_pk_add_f32 v[18:19], v[18:19], 1.0 op_sel_hi:[1,0]
	v_pk_add_f32 v[20:21], v[20:21], 1.0 op_sel_hi:[1,0]
	v_rcp_f32_e32 v201, v22
	v_rcp_f32_e32 v204, v23
	v_rcp_f32_e32 v205, v24
	v_rcp_f32_e32 v225, v25
; #define NTS(v, p) __builtin_nontemporal_store((v), (f32x4*)(p))
; __device__ __forceinline__ float sigmoidf_(float x) { return 1.0f / (1.0f + __expf(-x)); }
;     __device__ __forceinline__ void operator()(AccT& acc, const Unit& u, int wr, int wc, int fr, int fq) const {
;     ...
;                 f32x4 g0 = acc[ai][bj][m][0] * rstd + b0, g1 = acc[ai][bj][m][1] * rstd + b1;
; #pragma unroll
;                 for (int j = 0; j < 4; ++j) { g0[j] = sigmoidf_(g0[j]); g1[j] = sigmoidf_(g1[j]); }
;                 const f32x4 v0 = hv[r & 1][2 * bj] + p0 * g0, v1 = hv[r & 1][2 * bj + 1] + p1 * g1;
;                 NTS(v0, hp + bj * 128); NTS(v1, hp + bj * 128 + 4);
; #pragma unroll
;                 for (int j = 0; j < 4; ++j) ss += v0[j] * v0[j] + v1[j] * v1[j]; }
;             ss += __shfl_xor(ss, 16); ss += __shfl_xor(ss, 32);
;             if (fq == 0) unsafeAtomicAdd(rss3 + row, ss); __builtin_amdgcn_sched_barrier(0); }
	v_rcp_f32_e32 v226, v18
	v_rcp_f32_e32 v227, v19
	v_rcp_f32_e32 v228, v20
	v_rcp_f32_e32 v229, v21
	v_fma_f32 v22, -v22, v201, 1.0
	v_fma_f32 v23, -v23, v204, 1.0
	v_fma_f32 v24, -v24, v205, 1.0
	v_fma_f32 v25, -v25, v225, 1.0
	v_fma_f32 v18, -v18, v226, 1.0
	v_fma_f32 v19, -v19, v227, 1.0
	v_fma_f32 v20, -v20, v228, 1.0
	v_fma_f32 v21, -v21, v229, 1.0
	v_fma_f32 v22, v22, v201, v201
	v_fma_f32 v23, v23, v204, v204
	v_fma_f32 v24, v24, v205, v205
	v_fma_f32 v25, v25, v225, v225
	v_fma_f32 v18, v18, v226, v226
	v_fma_f32 v19, v19, v227, v227
	v_fma_f32 v20, v20, v228, v228
	v_fma_f32 v21, v21, v229, v229
	v_pk_fma_f32 v[14:15], v[14:15], v[172:173], v[240:241] op_sel:[0,1,0] op_sel_hi:[1,1,1]
	v_pk_fma_f32 v[16:17], v[16:17], v[172:173], v[242:243] op_sel:[0,1,0] op_sel_hi:[1,1,1]
	v_pk_fma_f32 v[10:11], v[10:11], v[172:173], v[244:245] op_sel:[0,1,0] op_sel_hi:[1,1,1]
	v_pk_fma_f32 v[12:13], v[12:13], v[172:173], v[246:247] op_sel:[0,1,0] op_sel_hi:[1,1,1]
	v_pk_mul_f32 v[14:15], v[14:15], v[206:207]
	v_pk_mul_f32 v[16:17], v[16:17], v[206:207]
	v_pk_mul_f32 v[10:11], v[10:11], v[206:207]
	v_pk_mul_f32 v[12:13], v[12:13], v[206:207]
	v_exp_f32_e32 v14, v14
	v_exp_f32_e32 v15, v15
	v_exp_f32_e32 v16, v16
	v_exp_f32_e32 v17, v17
	v_exp_f32_e32 v10, v10
	v_exp_f32_e32 v11, v11
	v_exp_f32_e32 v12, v12
	v_exp_f32_e32 v13, v13
	v_pk_add_f32 v[14:15], v[14:15], 1.0 op_sel_hi:[1,0]
	v_pk_add_f32 v[16:17], v[16:17], 1.0 op_sel_hi:[1,0]
	v_pk_add_f32 v[10:11], v[10:11], 1.0 op_sel_hi:[1,0]
	v_pk_add_f32 v[12:13], v[12:13], 1.0 op_sel_hi:[1,0]
	v_rcp_f32_e32 v201, v14
	v_rcp_f32_e32 v204, v15
	v_rcp_f32_e32 v205, v16
	v_rcp_f32_e32 v225, v17
	v_rcp_f32_e32 v226, v10
	v_rcp_f32_e32 v227, v11
	v_rcp_f32_e32 v228, v12
	v_rcp_f32_e32 v229, v13
	v_fma_f32 v14, -v14, v201, 1.0
	v_fma_f32 v15, -v15, v204, 1.0
	v_fma_f32 v16, -v16, v205, 1.0
	v_fma_f32 v17, -v17, v225, 1.0
	v_fma_f32 v10, -v10, v226, 1.0
	v_fma_f32 v11, -v11, v227, 1.0
	v_fma_f32 v12, -v12, v228, 1.0
	v_fma_f32 v13, -v13, v229, 1.0
	v_fma_f32 v14, v14, v201, v201
	v_fma_f32 v15, v15, v204, v204
	v_fma_f32 v16, v16, v205, v205
	v_fma_f32 v17, v17, v225, v225
	v_fma_f32 v10, v10, v226, v226
	v_fma_f32 v11, v11, v227, v227
	v_fma_f32 v12, v12, v228, v228
	v_fma_f32 v13, v13, v229, v229
	v_pk_fma_f32 v[6:7], v[6:7], v[172:173], v[248:249] op_sel:[0,1,0] op_sel_hi:[1,1,1]
	v_pk_fma_f32 v[8:9], v[8:9], v[172:173], v[250:251] op_sel:[0,1,0] op_sel_hi:[1,1,1]
	v_pk_fma_f32 v[2:3], v[2:3], v[172:173], v[232:233] op_sel:[0,1,0] op_sel_hi:[1,1,1]
	v_pk_fma_f32 v[4:5], v[4:5], v[172:173], v[234:235] op_sel:[0,1,0] op_sel_hi:[1,1,1]
	v_pk_mul_f32 v[6:7], v[6:7], v[206:207]
	v_pk_mul_f32 v[8:9], v[8:9], v[206:207]
	v_pk_mul_f32 v[2:3], v[2:3], v[206:207]
	v_pk_mul_f32 v[4:5], v[4:5], v[206:207]
	v_exp_f32_e32 v6, v6
	v_exp_f32_e32 v7, v7
	v_exp_f32_e32 v8, v8
	v_exp_f32_e32 v9, v9
	v_exp_f32_e32 v2, v2
	v_exp_f32_e32 v3, v3
	v_exp_f32_e32 v4, v4
	v_exp_f32_e32 v5, v5
	v_pk_add_f32 v[6:7], v[6:7], 1.0 op_sel_hi:[1,0]
	v_pk_add_f32 v[8:9], v[8:9], 1.0 op_sel_hi:[1,0]
	v_pk_add_f32 v[2:3], v[2:3], 1.0 op_sel_hi:[1,0]
	v_pk_add_f32 v[4:5], v[4:5], 1.0 op_sel_hi:[1,0]
	v_rcp_f32_e32 v201, v6
	v_rcp_f32_e32 v204, v7
	v_rcp_f32_e32 v205, v8
	v_rcp_f32_e32 v225, v9
	v_rcp_f32_e32 v226, v2
	v_rcp_f32_e32 v227, v3
	v_rcp_f32_e32 v228, v4
	v_rcp_f32_e32 v229, v5
	v_fma_f32 v6, -v6, v201, 1.0
	v_fma_f32 v7, -v7, v204, 1.0
	v_fma_f32 v8, -v8, v205, 1.0
	v_fma_f32 v9, -v9, v225, 1.0
	v_fma_f32 v2, -v2, v226, 1.0
	v_fma_f32 v3, -v3, v227, 1.0
	v_fma_f32 v4, -v4, v228, 1.0
	v_fma_f32 v5, -v5, v229, 1.0
	v_fma_f32 v6, v6, v201, v201
	v_fma_f32 v7, v7, v204, v204
	v_fma_f32 v8, v8, v205, v205
	v_fma_f32 v9, v9, v225, v225
	v_fma_f32 v2, v2, v226, v226
	v_fma_f32 v3, v3, v227, v227
	v_fma_f32 v4, v4, v228, v228
	v_fma_f32 v5, v5, v229, v229
	v_lshlrev_b32_e32 v204, 3, v222
	v_add_u32_e32 v204, s0, v204
	v_lshlrev_b32_e32 v204, 2, v204
	v_add_u32_e32 v201, s79, v169
	v_lshlrev_b32_e32 v201, 9, v201
	v_lshl_add_u32 v201, v222, 4, v201
	s_add_u32 s64, s2, 0x2000
	s_addc_u32 s65, s3, 0
	global_load_dwordx4 v[154:157], v201, s[64:65]
	global_load_dwordx4 v[158:161], v201, s[64:65] offset:256
	v_xor_b32_e32 v225, 16, v203
	v_xor_b32_e32 v226, 32, v203
	v_xor_b32_e32 v227, 48, v203
	v_lshlrev_b32_e32 v225, 2, v225
	v_lshlrev_b32_e32 v226, 2, v226
	v_lshlrev_b32_e32 v227, 2, v227
	v_cmp_eq_u32_e64 s[42:43], 0, v222
	s_waitcnt vmcnt(6)
	v_lshlrev_b32_e32 v164, 16, v146
	v_and_b32_e32 v165, 0xffff0000, v146
	v_lshlrev_b32_e32 v166, 16, v147
	v_and_b32_e32 v167, 0xffff0000, v147
	v_fma_f32 v122, v164, v122, v130
	v_fma_f32 v123, v165, v123, v131
	v_fma_f32 v124, v166, v124, v132
	v_fma_f32 v125, v167, v125, v133
	v_pk_mul_f32 v[228:229], v[122:123], v[122:123]
	s_nop 0
	v_pk_fma_f32 v[228:229], v[124:125], v[124:125], v[228:229]
	v_lshlrev_b32_e32 v170, 16, v148
	v_and_b32_e32 v171, 0xffff0000, v148
	v_lshlrev_b32_e32 v172, 16, v149
	v_and_b32_e32 v173, 0xffff0000, v149
	v_fma_f32 v114, v170, v114, v134
	v_fma_f32 v115, v171, v115, v135
	v_fma_f32 v116, v172, v116, v136
	v_fma_f32 v117, v173, v117, v137
	v_pk_fma_f32 v[228:229], v[114:115], v[114:115], v[228:229]
	s_nop 0
	v_pk_fma_f32 v[228:229], v[116:117], v[116:117], v[228:229]
	v_lshlrev_b32_e32 v164, 16, v150
	v_and_b32_e32 v165, 0xffff0000, v150
	v_lshlrev_b32_e32 v166, 16, v151
	v_and_b32_e32 v167, 0xffff0000, v151
	v_fma_f32 v110, v164, v110, v138
	v_fma_f32 v111, v165, v111, v139
	v_fma_f32 v112, v166, v112, v140
	v_fma_f32 v113, v167, v113, v141
	v_pk_fma_f32 v[228:229], v[110:111], v[110:111], v[228:229]
	s_nop 0
	v_pk_fma_f32 v[228:229], v[112:113], v[112:113], v[228:229]
	v_lshlrev_b32_e32 v170, 16, v152
	v_and_b32_e32 v171, 0xffff0000, v152
	v_lshlrev_b32_e32 v172, 16, v153
	v_and_b32_e32 v173, 0xffff0000, v153
	v_fma_f32 v106, v170, v106, v142
	v_fma_f32 v107, v171, v107, v143
	v_fma_f32 v108, v172, v108, v144
	v_fma_f32 v109, v173, v109, v145
	v_pk_fma_f32 v[228:229], v[106:107], v[106:107], v[228:229]
	s_nop 0
	v_pk_fma_f32 v[228:229], v[108:109], v[108:109], v[228:229]
	s_add_u32 s62, s22, 0x20000
	s_addc_u32 s63, s23, 0
	global_load_dwordx4 v[130:133], v200, s[62:63] nt
	global_load_dwordx4 v[134:137], v200, s[62:63] offset:16 nt
	global_load_dwordx4 v[138:141], v200, s[62:63] offset:512 nt
	global_load_dwordx4 v[142:145], v200, s[62:63] offset:528 nt
	s_add_u32 s64, s2, 0x4000
	s_addc_u32 s65, s3, 0
	global_load_dwordx4 v[146:149], v201, s[64:65]
	global_load_dwordx4 v[150:153], v201, s[64:65] offset:256
	s_nop 0
	v_add_f32_e32 v228, v228, v229
	ds_bpermute_b32 v229, v225, v228
	ds_bpermute_b32 v205, v226, v228
	ds_bpermute_b32 v206, v227, v228
	s_waitcnt lgkmcnt(0)
; #define NTL(p) __builtin_nontemporal_load((const f32x4*)(p))
; #define NTS(v, p) __builtin_nontemporal_store((v), (f32x4*)(p))
; __device__ __forceinline__ float bf_lo(unsigned w) { return __uint_as_float(w << 16); }
; __device__ __forceinline__ float bf_hi(unsigned w) { return __uint_as_float(w & 0xffff0000u); }
; __device__ __forceinline__ float sigmoidf_(float x) { return 1.0f / (1.0f + __expf(-x)); }
;     __device__ __forceinline__ void operator()(AccT& acc, const Unit& u, int wr, int wc, int fr, int fq) const {
;     ...
;             if (r < 7) { const int rn = row0 + ((r + 1) >> 2) * 128 + ((r + 1) & 3) * 16; const float* hn = H + (size_t)rn * DM + col0; const bf16_t* pn = ppbase + (((r + 1) >> 2) * 128 + ((r + 1) & 3) * 16) * 256;
;                 hv[(r + 1) & 1][0] = NTL(hn); hv[(r + 1) & 1][1] = NTL(hn + 4); hv[(r + 1) & 1][2] = NTL(hn + 128); hv[(r + 1) & 1][3] = NTL(hn + 132);
;                 pv[(r + 1) & 1][0] = *(const u32x4*)pn; pv[(r + 1) & 1][1] = *(const u32x4*)(pn + 128); rs[(r + 1) & 1] = rss2[rn]; }
;             float* hp = H + (size_t)row * DM + col0; float ss = 0.f; const float rstd = rsqrtf(rs[r & 1] * (1.0f / DM) + 1e-6f);
; #pragma unroll
;             for (int bj = 0; bj < 2; ++bj) { const u32x4 pw = pv[r & 1][bj];
;                 const f32x4 b0 = *(const f32x4*)(bias + col0 + bj * 128), b1 = *(const f32x4*)(bias + col0 + bj * 128 + 4);
;                 const f32x4 p0 = (f32x4){bf_lo(pw.x), bf_hi(pw.x), bf_lo(pw.y), bf_hi(pw.y)}, p1 = (f32x4){bf_lo(pw.z), bf_hi(pw.z), bf_lo(pw.w), bf_hi(pw.w)};
;                 f32x4 g0 = acc[ai][bj][m][0] * rstd + b0, g1 = acc[ai][bj][m][1] * rstd + b1;
; #pragma unroll
;                 for (int j = 0; j < 4; ++j) { g0[j] = sigmoidf_(g0[j]); g1[j] = sigmoidf_(g1[j]); }
;                 const f32x4 v0 = hv[r & 1][2 * bj] + p0 * g0, v1 = hv[r & 1][2 * bj + 1] + p1 * g1;
;                 NTS(v0, hp + bj * 128); NTS(v1, hp + bj * 128 + 4);
; #pragma unroll
;                 for (int j = 0; j < 4; ++j) ss += v0[j] * v0[j] + v1[j] * v1[j]; }
;             ss += __shfl_xor(ss, 16); ss += __shfl_xor(ss, 32);
;             if (fq == 0) unsafeAtomicAdd(rss3 + row, ss); __builtin_amdgcn_sched_barrier(0); }
	v_add_f32_e32 v228, v228, v229
	v_add_f32_e32 v205, v205, v206
	v_add_f32_e32 v228, v228, v205
	s_mov_b64 s[66:67], exec
	s_and_b64 exec, exec, s[42:43]
	global_atomic_add_f32 v207, v202, v228, s[36:37] sc0
	s_mov_b64 exec, s[66:67]
	s_waitcnt vmcnt(7)
	v_lshlrev_b32_e32 v164, 16, v154
	v_and_b32_e32 v165, 0xffff0000, v154
	v_lshlrev_b32_e32 v166, 16, v155
	v_and_b32_e32 v167, 0xffff0000, v155
	v_fma_f32 v126, v164, v126, v184
	v_fma_f32 v127, v165, v127, v185
	v_fma_f32 v128, v166, v128, v186
	v_fma_f32 v129, v167, v129, v187
	v_pk_mul_f32 v[228:229], v[126:127], v[126:127]
	s_nop 0
	v_pk_fma_f32 v[228:229], v[128:129], v[128:129], v[228:229]
	v_lshlrev_b32_e32 v170, 16, v156
	v_and_b32_e32 v171, 0xffff0000, v156
	v_lshlrev_b32_e32 v172, 16, v157
	v_and_b32_e32 v173, 0xffff0000, v157
	v_fma_f32 v118, v170, v118, v188
	v_fma_f32 v119, v171, v119, v189
	v_fma_f32 v120, v172, v120, v190
	v_fma_f32 v121, v173, v121, v191
	v_pk_fma_f32 v[228:229], v[118:119], v[118:119], v[228:229]
	s_nop 0
	v_pk_fma_f32 v[228:229], v[120:121], v[120:121], v[228:229]
	v_lshlrev_b32_e32 v164, 16, v158
	v_and_b32_e32 v165, 0xffff0000, v158
	v_lshlrev_b32_e32 v166, 16, v159
	v_and_b32_e32 v167, 0xffff0000, v159
	v_fma_f32 v102, v164, v102, v192
	v_fma_f32 v103, v165, v103, v193
	v_fma_f32 v104, v166, v104, v194
	v_fma_f32 v105, v167, v105, v195
	v_pk_fma_f32 v[228:229], v[102:103], v[102:103], v[228:229]
	s_nop 0
	v_pk_fma_f32 v[228:229], v[104:105], v[104:105], v[228:229]
	v_lshlrev_b32_e32 v170, 16, v160
	v_and_b32_e32 v171, 0xffff0000, v160
	v_lshlrev_b32_e32 v172, 16, v161
	v_and_b32_e32 v173, 0xffff0000, v161
	v_fma_f32 v98, v170, v98, v196
	v_fma_f32 v99, v171, v99, v197
	v_fma_f32 v100, v172, v100, v198
	v_fma_f32 v101, v173, v101, v199
	v_pk_fma_f32 v[228:229], v[98:99], v[98:99], v[228:229]
	s_nop 0
	v_pk_fma_f32 v[228:229], v[100:101], v[100:101], v[228:229]
	s_add_u32 s62, s22, 0x30000
	s_addc_u32 s63, s23, 0
	global_load_dwordx4 v[184:187], v200, s[62:63] nt
	global_load_dwordx4 v[188:191], v200, s[62:63] offset:16 nt
	global_load_dwordx4 v[192:195], v200, s[62:63] offset:512 nt
	global_load_dwordx4 v[196:199], v200, s[62:63] offset:528 nt
	s_add_u32 s64, s2, 0x6000
	s_addc_u32 s65, s3, 0
	global_load_dwordx4 v[154:157], v201, s[64:65]
	global_load_dwordx4 v[158:161], v201, s[64:65] offset:256
	s_nop 0
	v_add_f32_e32 v228, v228, v229
	ds_bpermute_b32 v229, v225, v228
	ds_bpermute_b32 v205, v226, v228
	ds_bpermute_b32 v206, v227, v228
	s_waitcnt lgkmcnt(0)
	v_add_f32_e32 v228, v228, v229
	v_add_f32_e32 v205, v205, v206
	v_add_f32_e32 v228, v228, v205
	s_mov_b64 s[66:67], exec
	s_and_b64 exec, exec, s[42:43]
	global_atomic_add_f32 v207, v202, v228, s[36:37] offset:64 sc0
	s_mov_b64 exec, s[66:67]
	s_waitcnt vmcnt(8)
	v_lshlrev_b32_e32 v164, 16, v146
	v_and_b32_e32 v165, 0xffff0000, v146
	v_lshlrev_b32_e32 v166, 16, v147
	v_and_b32_e32 v167, 0xffff0000, v147
	v_fma_f32 v94, v164, v94, v130
	v_fma_f32 v95, v165, v95, v131
	v_fma_f32 v96, v166, v96, v132
	v_fma_f32 v97, v167, v97, v133
	v_pk_mul_f32 v[228:229], v[94:95], v[94:95]
	s_nop 0
	v_pk_fma_f32 v[228:229], v[96:97], v[96:97], v[228:229]
	v_lshlrev_b32_e32 v170, 16, v148
	v_and_b32_e32 v171, 0xffff0000, v148
	v_lshlrev_b32_e32 v172, 16, v149
	v_and_b32_e32 v173, 0xffff0000, v149
	v_fma_f32 v90, v170, v90, v134
	v_fma_f32 v91, v171, v91, v135
	v_fma_f32 v92, v172, v92, v136
	v_fma_f32 v93, v173, v93, v137
	v_pk_fma_f32 v[228:229], v[90:91], v[90:91], v[228:229]
	s_nop 0
	v_pk_fma_f32 v[228:229], v[92:93], v[92:93], v[228:229]
	v_lshlrev_b32_e32 v164, 16, v150
	v_and_b32_e32 v165, 0xffff0000, v150
	v_lshlrev_b32_e32 v166, 16, v151
	v_and_b32_e32 v167, 0xffff0000, v151
	v_fma_f32 v86, v164, v86, v138
	v_fma_f32 v87, v165, v87, v139
	v_fma_f32 v88, v166, v88, v140
	v_fma_f32 v89, v167, v89, v141
	v_pk_fma_f32 v[228:229], v[86:87], v[86:87], v[228:229]
	s_nop 0
	v_pk_fma_f32 v[228:229], v[88:89], v[88:89], v[228:229]
	v_lshlrev_b32_e32 v170, 16, v152
	v_and_b32_e32 v171, 0xffff0000, v152
	v_lshlrev_b32_e32 v172, 16, v153
	v_and_b32_e32 v173, 0xffff0000, v153
	v_fma_f32 v82, v170, v82, v142
	v_fma_f32 v83, v171, v83, v143
	v_fma_f32 v84, v172, v84, v144
	v_fma_f32 v85, v173, v85, v145
	v_pk_fma_f32 v[228:229], v[82:83], v[82:83], v[228:229]
	s_nop 0
	v_pk_fma_f32 v[228:229], v[84:85], v[84:85], v[228:229]
	s_add_u32 s62, s22, 0x80000
	s_addc_u32 s63, s23, 0
	global_load_dwordx4 v[130:133], v200, s[62:63] nt
	global_load_dwordx4 v[134:137], v200, s[62:63] offset:16 nt
	global_load_dwordx4 v[138:141], v200, s[62:63] offset:512 nt
	global_load_dwordx4 v[142:145], v200, s[62:63] offset:528 nt
	s_add_u32 s64, s2, 0x10000
	s_addc_u32 s65, s3, 0
	global_load_dwordx4 v[146:149], v201, s[64:65]
	global_load_dwordx4 v[150:153], v201, s[64:65] offset:256
	s_nop 0
	v_add_f32_e32 v228, v228, v229
	ds_bpermute_b32 v229, v225, v228
	ds_bpermute_b32 v205, v226, v228
	ds_bpermute_b32 v206, v227, v228
	s_waitcnt lgkmcnt(0)
	v_add_f32_e32 v228, v228, v229
	v_add_f32_e32 v205, v205, v206
	v_add_f32_e32 v228, v228, v205
	s_mov_b64 s[66:67], exec
	s_and_b64 exec, exec, s[42:43]
	global_atomic_add_f32 v207, v202, v228, s[36:37] offset:128 sc0
	s_mov_b64 exec, s[66:67]
	s_waitcnt vmcnt(8)
; #define NTL(p) __builtin_nontemporal_load((const f32x4*)(p))
; #define NTS(v, p) __builtin_nontemporal_store((v), (f32x4*)(p))
; __device__ __forceinline__ float bf_lo(unsigned w) { return __uint_as_float(w << 16); }
; __device__ __forceinline__ float bf_hi(unsigned w) { return __uint_as_float(w & 0xffff0000u); }
; __device__ __forceinline__ float sigmoidf_(float x) { return 1.0f / (1.0f + __expf(-x)); }
;     __device__ __forceinline__ void operator()(AccT& acc, const Unit& u, int wr, int wc, int fr, int fq) const {
;     ...
;             if (r < 7) { const int rn = row0 + ((r + 1) >> 2) * 128 + ((r + 1) & 3) * 16; const float* hn = H + (size_t)rn * DM + col0; const bf16_t* pn = ppbase + (((r + 1) >> 2) * 128 + ((r + 1) & 3) * 16) * 256;
;                 hv[(r + 1) & 1][0] = NTL(hn); hv[(r + 1) & 1][1] = NTL(hn + 4); hv[(r + 1) & 1][2] = NTL(hn + 128); hv[(r + 1) & 1][3] = NTL(hn + 132);
;                 pv[(r + 1) & 1][0] = *(const u32x4*)pn; pv[(r + 1) & 1][1] = *(const u32x4*)(pn + 128); rs[(r + 1) & 1] = rss2[rn]; }
;             float* hp = H + (size_t)row * DM + col0; float ss = 0.f; const float rstd = rsqrtf(rs[r & 1] * (1.0f / DM) + 1e-6f);
; #pragma unroll
;             for (int bj = 0; bj < 2; ++bj) { const u32x4 pw = pv[r & 1][bj];
;                 const f32x4 b0 = *(const f32x4*)(bias + col0 + bj * 128), b1 = *(const f32x4*)(bias + col0 + bj * 128 + 4);
;                 const f32x4 p0 = (f32x4){bf_lo(pw.x), bf_hi(pw.x), bf_lo(pw.y), bf_hi(pw.y)}, p1 = (f32x4){bf_lo(pw.z), bf_hi(pw.z), bf_lo(pw.w), bf_hi(pw.w)};
;                 f32x4 g0 = acc[ai][bj][m][0] * rstd + b0, g1 = acc[ai][bj][m][1] * rstd + b1;
; #pragma unroll
;                 for (int j = 0; j < 4; ++j) { g0[j] = sigmoidf_(g0[j]); g1[j] = sigmoidf_(g1[j]); }
;                 const f32x4 v0 = hv[r & 1][2 * bj] + p0 * g0, v1 = hv[r & 1][2 * bj + 1] + p1 * g1;
;                 NTS(v0, hp + bj * 128); NTS(v1, hp + bj * 128 + 4);
; #pragma unroll
;                 for (int j = 0; j < 4; ++j) ss += v0[j] * v0[j] + v1[j] * v1[j]; }
;             ss += __shfl_xor(ss, 16); ss += __shfl_xor(ss, 32);
;             if (fq == 0) unsafeAtomicAdd(rss3 + row, ss); __builtin_amdgcn_sched_barrier(0); }
	v_lshlrev_b32_e32 v164, 16, v154
	v_and_b32_e32 v165, 0xffff0000, v154
	v_lshlrev_b32_e32 v166, 16, v155
	v_and_b32_e32 v167, 0xffff0000, v155
	v_fma_f32 v78, v164, v78, v184
	v_fma_f32 v79, v165, v79, v185
	v_fma_f32 v80, v166, v80, v186
	v_fma_f32 v81, v167, v81, v187
	v_pk_mul_f32 v[228:229], v[78:79], v[78:79]
	s_nop 0
	v_pk_fma_f32 v[228:229], v[80:81], v[80:81], v[228:229]
	v_lshlrev_b32_e32 v170, 16, v156
	v_and_b32_e32 v171, 0xffff0000, v156
	v_lshlrev_b32_e32 v172, 16, v157
	v_and_b32_e32 v173, 0xffff0000, v157
	v_fma_f32 v74, v170, v74, v188
	v_fma_f32 v75, v171, v75, v189
	v_fma_f32 v76, v172, v76, v190
	v_fma_f32 v77, v173, v77, v191
	v_pk_fma_f32 v[228:229], v[74:75], v[74:75], v[228:229]
	s_nop 0
	v_pk_fma_f32 v[228:229], v[76:77], v[76:77], v[228:229]
	v_lshlrev_b32_e32 v164, 16, v158
	v_and_b32_e32 v165, 0xffff0000, v158
	v_lshlrev_b32_e32 v166, 16, v159
	v_and_b32_e32 v167, 0xffff0000, v159
	v_fma_f32 v70, v164, v70, v192
	v_fma_f32 v71, v165, v71, v193
	v_fma_f32 v72, v166, v72, v194
	v_fma_f32 v73, v167, v73, v195
	v_pk_fma_f32 v[228:229], v[70:71], v[70:71], v[228:229]
	s_nop 0
	v_pk_fma_f32 v[228:229], v[72:73], v[72:73], v[228:229]
	v_lshlrev_b32_e32 v170, 16, v160
	v_and_b32_e32 v171, 0xffff0000, v160
	v_lshlrev_b32_e32 v172, 16, v161
	v_and_b32_e32 v173, 0xffff0000, v161
	v_fma_f32 v66, v170, v66, v196
	v_fma_f32 v67, v171, v67, v197
	v_fma_f32 v68, v172, v68, v198
	v_fma_f32 v69, v173, v69, v199
	v_pk_fma_f32 v[228:229], v[66:67], v[66:67], v[228:229]
	s_nop 0
	v_pk_fma_f32 v[228:229], v[68:69], v[68:69], v[228:229]
	s_add_u32 s62, s22, 0x90000
	s_addc_u32 s63, s23, 0
	global_load_dwordx4 v[184:187], v200, s[62:63] nt
	global_load_dwordx4 v[188:191], v200, s[62:63] offset:16 nt
	global_load_dwordx4 v[192:195], v200, s[62:63] offset:512 nt
	global_load_dwordx4 v[196:199], v200, s[62:63] offset:528 nt
	s_add_u32 s64, s2, 0x12000
	s_addc_u32 s65, s3, 0
	global_load_dwordx4 v[154:157], v201, s[64:65]
	global_load_dwordx4 v[158:161], v201, s[64:65] offset:256
	s_nop 0
	v_add_f32_e32 v228, v228, v229
	ds_bpermute_b32 v229, v225, v228
	ds_bpermute_b32 v205, v226, v228
	ds_bpermute_b32 v206, v227, v228
	s_waitcnt lgkmcnt(0)
	v_add_f32_e32 v228, v228, v229
	v_add_f32_e32 v205, v205, v206
	v_add_f32_e32 v228, v228, v205
	s_mov_b64 s[66:67], exec
	s_and_b64 exec, exec, s[42:43]
	global_atomic_add_f32 v207, v202, v228, s[36:37] offset:192 sc0
	s_mov_b64 exec, s[66:67]
	s_waitcnt vmcnt(8)
	v_lshlrev_b32_e32 v164, 16, v146
	v_and_b32_e32 v165, 0xffff0000, v146
	v_lshlrev_b32_e32 v166, 16, v147
	v_and_b32_e32 v167, 0xffff0000, v147
	v_fma_f32 v62, v164, v62, v130
	v_fma_f32 v63, v165, v63, v131
	v_fma_f32 v64, v166, v64, v132
	v_fma_f32 v65, v167, v65, v133
	v_pk_mul_f32 v[228:229], v[62:63], v[62:63]
	s_nop 0
	v_pk_fma_f32 v[228:229], v[64:65], v[64:65], v[228:229]
	v_lshlrev_b32_e32 v170, 16, v148
	v_and_b32_e32 v171, 0xffff0000, v148
	v_lshlrev_b32_e32 v172, 16, v149
	v_and_b32_e32 v173, 0xffff0000, v149
	v_fma_f32 v58, v170, v58, v134
	v_fma_f32 v59, v171, v59, v135
	v_fma_f32 v60, v172, v60, v136
	v_fma_f32 v61, v173, v61, v137
	v_pk_fma_f32 v[228:229], v[58:59], v[58:59], v[228:229]
	s_nop 0
	v_pk_fma_f32 v[228:229], v[60:61], v[60:61], v[228:229]
	v_lshlrev_b32_e32 v164, 16, v150
	v_and_b32_e32 v165, 0xffff0000, v150
	v_lshlrev_b32_e32 v166, 16, v151
	v_and_b32_e32 v167, 0xffff0000, v151
	v_fma_f32 v54, v164, v54, v138
	v_fma_f32 v55, v165, v55, v139
	v_fma_f32 v56, v166, v56, v140
	v_fma_f32 v57, v167, v57, v141
	v_pk_fma_f32 v[228:229], v[54:55], v[54:55], v[228:229]
	s_nop 0
	v_pk_fma_f32 v[228:229], v[56:57], v[56:57], v[228:229]
	v_lshlrev_b32_e32 v170, 16, v152
	v_and_b32_e32 v171, 0xffff0000, v152
	v_lshlrev_b32_e32 v172, 16, v153
	v_and_b32_e32 v173, 0xffff0000, v153
	v_fma_f32 v50, v170, v50, v142
	v_fma_f32 v51, v171, v51, v143
	v_fma_f32 v52, v172, v52, v144
	v_fma_f32 v53, v173, v53, v145
	v_pk_fma_f32 v[228:229], v[50:51], v[50:51], v[228:229]
	s_nop 0
	v_pk_fma_f32 v[228:229], v[52:53], v[52:53], v[228:229]
	s_add_u32 s62, s22, 0xa0000
	s_addc_u32 s63, s23, 0
	global_load_dwordx4 v[130:133], v200, s[62:63] nt
	global_load_dwordx4 v[134:137], v200, s[62:63] offset:16 nt
	global_load_dwordx4 v[138:141], v200, s[62:63] offset:512 nt
	global_load_dwordx4 v[142:145], v200, s[62:63] offset:528 nt
	s_add_u32 s64, s2, 0x14000
	s_addc_u32 s65, s3, 0
	global_load_dwordx4 v[146:149], v201, s[64:65]
	global_load_dwordx4 v[150:153], v201, s[64:65] offset:256
	s_nop 0
	v_add_f32_e32 v228, v228, v229
	ds_bpermute_b32 v229, v225, v228
	ds_bpermute_b32 v205, v226, v228
	ds_bpermute_b32 v206, v227, v228
	s_waitcnt lgkmcnt(0)
	v_add_f32_e32 v228, v228, v229
	v_add_f32_e32 v205, v205, v206
	v_add_f32_e32 v228, v228, v205
	s_mov_b64 s[66:67], exec
	s_and_b64 exec, exec, s[42:43]
	global_atomic_add_f32 v207, v202, v228, s[36:37] offset:512 sc0
	s_mov_b64 exec, s[66:67]
	s_waitcnt vmcnt(8)
; #define NTS(v, p) __builtin_nontemporal_store((v), (f32x4*)(p))
;     __device__ __forceinline__ void operator()(AccT& acc, const Unit& u, int wr, int wc, int fr, int fq) const {
;     ...
;                 const f32x4 v0 = hv[r & 1][2 * bj] + p0 * g0, v1 = hv[r & 1][2 * bj + 1] + p1 * g1;
;                 NTS(v0, hp + bj * 128); NTS(v1, hp + bj * 128 + 4);
; #pragma unroll
;                 for (int j = 0; j < 4; ++j) ss += v0[j] * v0[j] + v1[j] * v1[j]; }
;             ss += __shfl_xor(ss, 16); ss += __shfl_xor(ss, 32);
;             if (fq == 0) unsafeAtomicAdd(rss3 + row, ss); __builtin_amdgcn_sched_barrier(0); }
	v_lshlrev_b32_e32 v164, 16, v154
	v_and_b32_e32 v165, 0xffff0000, v154
	v_lshlrev_b32_e32 v166, 16, v155
	v_and_b32_e32 v167, 0xffff0000, v155
	v_fma_f32 v46, v164, v46, v184
	v_fma_f32 v47, v165, v47, v185
	v_fma_f32 v48, v166, v48, v186
	v_fma_f32 v49, v167, v49, v187
	v_pk_mul_f32 v[228:229], v[46:47], v[46:47]
	s_nop 0
	v_pk_fma_f32 v[228:229], v[48:49], v[48:49], v[228:229]
	v_lshlrev_b32_e32 v170, 16, v156
	v_and_b32_e32 v171, 0xffff0000, v156
	v_lshlrev_b32_e32 v172, 16, v157
	v_and_b32_e32 v173, 0xffff0000, v157
	v_fma_f32 v42, v170, v42, v188
	v_fma_f32 v43, v171, v43, v189
	v_fma_f32 v44, v172, v44, v190
	v_fma_f32 v45, v173, v45, v191
	v_pk_fma_f32 v[228:229], v[42:43], v[42:43], v[228:229]
	s_nop 0
	v_pk_fma_f32 v[228:229], v[44:45], v[44:45], v[228:229]
	v_lshlrev_b32_e32 v164, 16, v158
	v_and_b32_e32 v165, 0xffff0000, v158
	v_lshlrev_b32_e32 v166, 16, v159
	v_and_b32_e32 v167, 0xffff0000, v159
	v_fma_f32 v38, v164, v38, v192
	v_fma_f32 v39, v165, v39, v193
	v_fma_f32 v40, v166, v40, v194
	v_fma_f32 v41, v167, v41, v195
	v_pk_fma_f32 v[228:229], v[38:39], v[38:39], v[228:229]
	s_nop 0
	v_pk_fma_f32 v[228:229], v[40:41], v[40:41], v[228:229]
	v_lshlrev_b32_e32 v170, 16, v160
	v_and_b32_e32 v171, 0xffff0000, v160
	v_lshlrev_b32_e32 v172, 16, v161
	v_and_b32_e32 v173, 0xffff0000, v161
	v_fma_f32 v34, v170, v34, v196
	v_fma_f32 v35, v171, v35, v197
	v_fma_f32 v36, v172, v36, v198
	v_fma_f32 v37, v173, v37, v199
	v_pk_fma_f32 v[228:229], v[34:35], v[34:35], v[228:229]
	s_nop 0
	v_pk_fma_f32 v[228:229], v[36:37], v[36:37], v[228:229]
	s_add_u32 s62, s22, 0xb0000
	s_addc_u32 s63, s23, 0
	global_load_dwordx4 v[184:187], v200, s[62:63] nt
	global_load_dwordx4 v[188:191], v200, s[62:63] offset:16 nt
	global_load_dwordx4 v[192:195], v200, s[62:63] offset:512 nt
	global_load_dwordx4 v[196:199], v200, s[62:63] offset:528 nt
	s_add_u32 s64, s2, 0x16000
	s_addc_u32 s65, s3, 0
	global_load_dwordx4 v[154:157], v201, s[64:65]
	global_load_dwordx4 v[158:161], v201, s[64:65] offset:256
	s_nop 0
	v_add_f32_e32 v228, v228, v229
	ds_bpermute_b32 v229, v225, v228
	ds_bpermute_b32 v205, v226, v228
	ds_bpermute_b32 v206, v227, v228
	s_waitcnt lgkmcnt(0)
	v_add_f32_e32 v228, v228, v229
	v_add_f32_e32 v205, v205, v206
	v_add_f32_e32 v228, v228, v205
	s_mov_b64 s[66:67], exec
	s_and_b64 exec, exec, s[42:43]
	global_atomic_add_f32 v207, v202, v228, s[36:37] offset:576 sc0
	s_mov_b64 exec, s[66:67]
	s_waitcnt vmcnt(8)
	v_lshlrev_b32_e32 v164, 16, v146
	v_and_b32_e32 v165, 0xffff0000, v146
	v_lshlrev_b32_e32 v166, 16, v147
	v_and_b32_e32 v167, 0xffff0000, v147
	v_fma_f32 v30, v164, v30, v130
	v_fma_f32 v31, v165, v31, v131
	v_fma_f32 v32, v166, v32, v132
	v_fma_f32 v33, v167, v33, v133
	v_pk_mul_f32 v[228:229], v[30:31], v[30:31]
	s_nop 0
	v_pk_fma_f32 v[228:229], v[32:33], v[32:33], v[228:229]
	v_lshlrev_b32_e32 v170, 16, v148
	v_and_b32_e32 v171, 0xffff0000, v148
	v_lshlrev_b32_e32 v172, 16, v149
	v_and_b32_e32 v173, 0xffff0000, v149
	v_fma_f32 v26, v170, v26, v134
	v_fma_f32 v27, v171, v27, v135
	v_fma_f32 v28, v172, v28, v136
	v_fma_f32 v29, v173, v29, v137
	v_pk_fma_f32 v[228:229], v[26:27], v[26:27], v[228:229]
	s_nop 0
	v_pk_fma_f32 v[228:229], v[28:29], v[28:29], v[228:229]
	v_lshlrev_b32_e32 v164, 16, v150
	v_and_b32_e32 v165, 0xffff0000, v150
	v_lshlrev_b32_e32 v166, 16, v151
	v_and_b32_e32 v167, 0xffff0000, v151
	v_fma_f32 v22, v164, v22, v138
	v_fma_f32 v23, v165, v23, v139
	v_fma_f32 v24, v166, v24, v140
	v_fma_f32 v25, v167, v25, v141
	v_pk_fma_f32 v[228:229], v[22:23], v[22:23], v[228:229]
	s_nop 0
	v_pk_fma_f32 v[228:229], v[24:25], v[24:25], v[228:229]
	v_lshlrev_b32_e32 v170, 16, v152
	v_and_b32_e32 v171, 0xffff0000, v152
	v_lshlrev_b32_e32 v172, 16, v153
	v_and_b32_e32 v173, 0xffff0000, v153
	v_fma_f32 v18, v170, v18, v142
	v_fma_f32 v19, v171, v19, v143
	v_fma_f32 v20, v172, v20, v144
	v_fma_f32 v21, v173, v21, v145
	v_pk_fma_f32 v[228:229], v[18:19], v[18:19], v[228:229]
	s_nop 0
	v_pk_fma_f32 v[228:229], v[20:21], v[20:21], v[228:229]
	s_nop 0
	v_add_f32_e32 v228, v228, v229
	ds_bpermute_b32 v229, v225, v228
	ds_bpermute_b32 v205, v226, v228
	ds_bpermute_b32 v206, v227, v228
	s_waitcnt lgkmcnt(0)
	v_add_f32_e32 v228, v228, v229
	v_add_f32_e32 v205, v205, v206
	v_add_f32_e32 v228, v228, v205
	s_mov_b64 s[66:67], exec
	s_and_b64 exec, exec, s[42:43]
	global_atomic_add_f32 v207, v202, v228, s[36:37] offset:640 sc0
	s_mov_b64 exec, s[66:67]
	s_waitcnt vmcnt(2)
	v_lshlrev_b32_e32 v164, 16, v154
	v_and_b32_e32 v165, 0xffff0000, v154
	v_lshlrev_b32_e32 v166, 16, v155
	v_and_b32_e32 v167, 0xffff0000, v155
	v_fma_f32 v14, v164, v14, v184
	v_fma_f32 v15, v165, v15, v185
	v_fma_f32 v16, v166, v16, v186
	v_fma_f32 v17, v167, v17, v187
	v_pk_mul_f32 v[228:229], v[14:15], v[14:15]
	s_nop 0
	v_pk_fma_f32 v[228:229], v[16:17], v[16:17], v[228:229]
	v_lshlrev_b32_e32 v170, 16, v156
	v_and_b32_e32 v171, 0xffff0000, v156
	v_lshlrev_b32_e32 v172, 16, v157
	v_and_b32_e32 v173, 0xffff0000, v157
	v_fma_f32 v10, v170, v10, v188
	v_fma_f32 v11, v171, v11, v189
	v_fma_f32 v12, v172, v12, v190
	v_fma_f32 v13, v173, v13, v191
	v_pk_fma_f32 v[228:229], v[10:11], v[10:11], v[228:229]
	s_nop 0
	v_pk_fma_f32 v[228:229], v[12:13], v[12:13], v[228:229]
	v_lshlrev_b32_e32 v164, 16, v158
	v_and_b32_e32 v165, 0xffff0000, v158
	v_lshlrev_b32_e32 v166, 16, v159
	v_and_b32_e32 v167, 0xffff0000, v159
	v_fma_f32 v6, v164, v6, v192
	v_fma_f32 v7, v165, v7, v193
	v_fma_f32 v8, v166, v8, v194
	v_fma_f32 v9, v167, v9, v195
	v_pk_fma_f32 v[228:229], v[6:7], v[6:7], v[228:229]
	s_nop 0
	v_pk_fma_f32 v[228:229], v[8:9], v[8:9], v[228:229]
	v_lshlrev_b32_e32 v170, 16, v160
	v_and_b32_e32 v171, 0xffff0000, v160
	v_lshlrev_b32_e32 v172, 16, v161
	v_and_b32_e32 v173, 0xffff0000, v161
	v_fma_f32 v2, v170, v2, v196
	v_fma_f32 v3, v171, v3, v197
	v_fma_f32 v4, v172, v4, v198
	v_fma_f32 v5, v173, v5, v199
	v_pk_fma_f32 v[228:229], v[2:3], v[2:3], v[228:229]
	s_nop 0
	v_pk_fma_f32 v[228:229], v[4:5], v[4:5], v[228:229]
	s_nop 0
	v_add_f32_e32 v228, v228, v229
	ds_bpermute_b32 v229, v225, v228
	ds_bpermute_b32 v205, v226, v228
	ds_bpermute_b32 v206, v227, v228
	s_waitcnt lgkmcnt(0)
	v_add_f32_e32 v228, v228, v229
	v_add_f32_e32 v205, v205, v206
	v_add_f32_e32 v228, v228, v205
	s_mov_b64 s[66:67], exec
	s_and_b64 exec, exec, s[42:43]
	global_atomic_add_f32 v207, v202, v228, s[36:37] offset:704 sc0
	s_mov_b64 exec, s[66:67]
	s_waitcnt vmcnt(0)
	s_barrier
	s_barrier
	s_lshr_b32 s60, s60, 8
	s_lshl_b32 s60, s60, 2
	s_add_u32 s62, s36, 0x20000
	s_addc_u32 s63, s37, 0
	s_add_u32 s62, s62, s60
	s_addc_u32 s63, s63, 0
	v_cmp_eq_u32_e32 vcc, 0, v162
	s_and_saveexec_b64 s[66:67], vcc
	s_cbranch_execz .Lpg_met
	v_mov_b32_e32 v205, 0
	v_mov_b32_e32 v228, 1
	global_atomic_add v229, v205, v228, s[62:63] sc0
	s_waitcnt vmcnt(0)
	s_mov_b32 s61, 0
;     __device__ __forceinline__ void operator()(AccT& acc, const Unit& u, int wr, int wc, int fr, int fq) const {
;     ...
;             ss += __shfl_xor(ss, 16); ss += __shfl_xor(ss, 32);
;             if (fq == 0) unsafeAtomicAdd(rss3 + row, ss); __builtin_amdgcn_sched_barrier(0); }
; __global__ void __launch_bounds__(512, 2) mega(Params P0) {
;     ...
;                 for (int j = 0; j < 16; ++j) { const int i = (ck * 16 + j) * 64 + lane; const int row = i >> 8, c4 = i & 255; const float rstd = rsqrtf(r3[row] * (1.0f / DM) + 1e-6f);
;                     __builtin_nontemporal_store(v[j] * rstd * *(const f32x4*)(fw + 4 * c4), (f32x4*)P.out + i); } } }
.Lpg_spin:
	global_load_dword v229, v205, s[62:63] sc1
	s_waitcnt vmcnt(0)
	v_readfirstlane_b32 s64, v229
	s_nop 3
	s_cmp_ge_u32 s64, 4
	s_cbranch_scc1 .Lpg_met
	s_sleep 1
	s_add_i32 s61, s61, 1
	s_cmp_lt_u32 s61, 0x4000
	s_cbranch_scc1 .Lpg_spin
.Lpg_met:
	s_or_b64 exec, exec, s[66:67]
	s_barrier
	s_barrier
	v_mov_b32_e32 v205, 0
	v_and_b32_e32 v229, 15, v203
	v_lshlrev_b32_e32 v229, 2, v229
	s_mov_b64 s[66:67], exec
	s_and_b64 exec, exec, s[42:43]
	global_atomic_add_f32 v164, v202, v205, s[36:37] sc0
	global_atomic_add_f32 v165, v202, v205, s[36:37] offset:64 sc0
	global_atomic_add_f32 v166, v202, v205, s[36:37] offset:128 sc0
	global_atomic_add_f32 v167, v202, v205, s[36:37] offset:192 sc0
	global_atomic_add_f32 v170, v202, v205, s[36:37] offset:512 sc0
	global_atomic_add_f32 v171, v202, v205, s[36:37] offset:576 sc0
	global_atomic_add_f32 v172, v202, v205, s[36:37] offset:640 sc0
	global_atomic_add_f32 v173, v202, v205, s[36:37] offset:704 sc0
	s_mov_b64 exec, s[66:67]
	global_load_dwordx4 v[240:243], v204, s[74:75]
	global_load_dwordx4 v[244:247], v204, s[74:75] offset:16
	global_load_dwordx4 v[248:251], v204, s[74:75] offset:512
	global_load_dwordx4 v[232:235], v204, s[74:75] offset:528
	s_waitcnt vmcnt(4)
	ds_bpermute_b32 v164, v229, v164
	ds_bpermute_b32 v165, v229, v165
	ds_bpermute_b32 v166, v229, v166
	ds_bpermute_b32 v167, v229, v167
	ds_bpermute_b32 v170, v229, v170
	ds_bpermute_b32 v171, v229, v171
	ds_bpermute_b32 v172, v229, v172
	ds_bpermute_b32 v173, v229, v173
	s_waitcnt lgkmcnt(0)
	v_fmamk_f32 v164, v164, 0x3a800000, v210
	v_fmamk_f32 v165, v165, 0x3a800000, v210
	v_fmamk_f32 v166, v166, 0x3a800000, v210
	v_fmamk_f32 v167, v167, 0x3a800000, v210
	v_fmamk_f32 v170, v170, 0x3a800000, v210
	v_fmamk_f32 v171, v171, 0x3a800000, v210
	v_fmamk_f32 v172, v172, 0x3a800000, v210
	v_fmamk_f32 v173, v173, 0x3a800000, v210
	v_mul_f32_e32 v130, 0x4b800000, v164
	v_mul_f32_e32 v131, 0x4b800000, v165
	v_mul_f32_e32 v132, 0x4b800000, v166
	v_mul_f32_e32 v133, 0x4b800000, v167
	v_mul_f32_e32 v134, 0x4b800000, v170
	v_mul_f32_e32 v135, 0x4b800000, v171
	v_mul_f32_e32 v136, 0x4b800000, v172
	v_mul_f32_e32 v137, 0x4b800000, v173
	v_cmp_gt_f32_e64 s[62:63], s30, v164
	v_cmp_gt_f32_e64 s[64:65], s30, v165
	v_cmp_gt_f32_e64 s[66:67], s30, v166
	v_cmp_gt_f32_e64 s[68:69], s30, v167
	s_nop 1
	v_cndmask_b32_e64 v164, v164, v130, s[62:63]
	v_cndmask_b32_e64 v165, v165, v131, s[64:65]
	v_cndmask_b32_e64 v166, v166, v132, s[66:67]
	v_cndmask_b32_e64 v167, v167, v133, s[68:69]
	v_rsq_f32_e32 v164, v164
	v_rsq_f32_e32 v165, v165
	v_rsq_f32_e32 v166, v166
	v_rsq_f32_e32 v167, v167
	s_nop 0
	v_mul_f32_e32 v130, 0x45800000, v164
	v_mul_f32_e32 v131, 0x45800000, v165
	v_mul_f32_e32 v132, 0x45800000, v166
	v_mul_f32_e32 v133, 0x45800000, v167
	v_cndmask_b32_e64 v164, v164, v130, s[62:63]
	v_cndmask_b32_e64 v165, v165, v131, s[64:65]
	v_cndmask_b32_e64 v166, v166, v132, s[66:67]
	v_cndmask_b32_e64 v167, v167, v133, s[68:69]
	v_cmp_gt_f32_e64 s[62:63], s30, v170
	v_cmp_gt_f32_e64 s[64:65], s30, v171
	v_cmp_gt_f32_e64 s[66:67], s30, v172
	v_cmp_gt_f32_e64 s[68:69], s30, v173
	s_nop 1
	v_cndmask_b32_e64 v170, v170, v134, s[62:63]
	v_cndmask_b32_e64 v171, v171, v135, s[64:65]
	v_cndmask_b32_e64 v172, v172, v136, s[66:67]
	v_cndmask_b32_e64 v173, v173, v137, s[68:69]
	v_rsq_f32_e32 v170, v170
	v_rsq_f32_e32 v171, v171
	v_rsq_f32_e32 v172, v172
	v_rsq_f32_e32 v173, v173
	s_nop 0
	v_mul_f32_e32 v134, 0x45800000, v170
	v_mul_f32_e32 v135, 0x45800000, v171
	v_mul_f32_e32 v136, 0x45800000, v172
	v_mul_f32_e32 v137, 0x45800000, v173
	v_cndmask_b32_e64 v170, v170, v134, s[62:63]
	v_cndmask_b32_e64 v171, v171, v135, s[64:65]
	v_cndmask_b32_e64 v172, v172, v136, s[66:67]
	v_cndmask_b32_e64 v173, v173, v137, s[68:69]
	s_waitcnt vmcnt(0)
	s_add_u32 s62, s52, 0x0
	s_addc_u32 s63, s53, 0
	v_pk_mul_f32 v[122:123], v[122:123], v[164:165] op_sel_hi:[1,0]
	v_pk_mul_f32 v[124:125], v[124:125], v[164:165] op_sel_hi:[1,0]
	v_pk_mul_f32 v[114:115], v[114:115], v[164:165] op_sel_hi:[1,0]
	v_pk_mul_f32 v[116:117], v[116:117], v[164:165] op_sel_hi:[1,0]
	v_pk_mul_f32 v[110:111], v[110:111], v[164:165] op_sel_hi:[1,0]
	v_pk_mul_f32 v[112:113], v[112:113], v[164:165] op_sel_hi:[1,0]
	v_pk_mul_f32 v[106:107], v[106:107], v[164:165] op_sel_hi:[1,0]
	v_pk_mul_f32 v[108:109], v[108:109], v[164:165] op_sel_hi:[1,0]
	v_pk_mul_f32 v[122:123], v[122:123], v[240:241]
	v_pk_mul_f32 v[124:125], v[124:125], v[242:243]
	v_pk_mul_f32 v[114:115], v[114:115], v[244:245]
	v_pk_mul_f32 v[116:117], v[116:117], v[246:247]
	v_pk_mul_f32 v[110:111], v[110:111], v[248:249]
	v_pk_mul_f32 v[112:113], v[112:113], v[250:251]
	v_pk_mul_f32 v[106:107], v[106:107], v[232:233]
	v_pk_mul_f32 v[108:109], v[108:109], v[234:235]
	global_store_dwordx4 v200, v[122:125], s[62:63] nt
	global_store_dwordx4 v200, v[114:117], s[62:63] offset:16 nt
	global_store_dwordx4 v200, v[110:113], s[62:63] offset:512 nt
	global_store_dwordx4 v200, v[106:109], s[62:63] offset:528 nt
	s_add_u32 s62, s52, 0x10000
	s_addc_u32 s63, s53, 0
	v_pk_mul_f32 v[126:127], v[126:127], v[164:165] op_sel:[0,1] op_sel_hi:[1,1]
	v_pk_mul_f32 v[128:129], v[128:129], v[164:165] op_sel:[0,1] op_sel_hi:[1,1]
	v_pk_mul_f32 v[118:119], v[118:119], v[164:165] op_sel:[0,1] op_sel_hi:[1,1]
	v_pk_mul_f32 v[120:121], v[120:121], v[164:165] op_sel:[0,1] op_sel_hi:[1,1]
	v_pk_mul_f32 v[102:103], v[102:103], v[164:165] op_sel:[0,1] op_sel_hi:[1,1]
	v_pk_mul_f32 v[104:105], v[104:105], v[164:165] op_sel:[0,1] op_sel_hi:[1,1]
	v_pk_mul_f32 v[98:99], v[98:99], v[164:165] op_sel:[0,1] op_sel_hi:[1,1]
	v_pk_mul_f32 v[100:101], v[100:101], v[164:165] op_sel:[0,1] op_sel_hi:[1,1]
; __global__ void __launch_bounds__(512, 2) mega(Params P0) {
;     ...
;                 for (int j = 0; j < 16; ++j) { const int i = (ck * 16 + j) * 64 + lane; const int row = i >> 8, c4 = i & 255; const float rstd = rsqrtf(r3[row] * (1.0f / DM) + 1e-6f);
;                     __builtin_nontemporal_store(v[j] * rstd * *(const f32x4*)(fw + 4 * c4), (f32x4*)P.out + i); } } }
	v_pk_mul_f32 v[126:127], v[126:127], v[240:241]
	v_pk_mul_f32 v[128:129], v[128:129], v[242:243]
	v_pk_mul_f32 v[118:119], v[118:119], v[244:245]
	v_pk_mul_f32 v[120:121], v[120:121], v[246:247]
	v_pk_mul_f32 v[102:103], v[102:103], v[248:249]
	v_pk_mul_f32 v[104:105], v[104:105], v[250:251]
	v_pk_mul_f32 v[98:99], v[98:99], v[232:233]
	v_pk_mul_f32 v[100:101], v[100:101], v[234:235]
	global_store_dwordx4 v200, v[126:129], s[62:63] nt
	global_store_dwordx4 v200, v[118:121], s[62:63] offset:16 nt
	global_store_dwordx4 v200, v[102:105], s[62:63] offset:512 nt
	global_store_dwordx4 v200, v[98:101], s[62:63] offset:528 nt
	s_add_u32 s62, s52, 0x20000
	s_addc_u32 s63, s53, 0
	v_pk_mul_f32 v[94:95], v[94:95], v[166:167] op_sel_hi:[1,0]
	v_pk_mul_f32 v[96:97], v[96:97], v[166:167] op_sel_hi:[1,0]
	v_pk_mul_f32 v[90:91], v[90:91], v[166:167] op_sel_hi:[1,0]
	v_pk_mul_f32 v[92:93], v[92:93], v[166:167] op_sel_hi:[1,0]
	v_pk_mul_f32 v[86:87], v[86:87], v[166:167] op_sel_hi:[1,0]
	v_pk_mul_f32 v[88:89], v[88:89], v[166:167] op_sel_hi:[1,0]
	v_pk_mul_f32 v[82:83], v[82:83], v[166:167] op_sel_hi:[1,0]
	v_pk_mul_f32 v[84:85], v[84:85], v[166:167] op_sel_hi:[1,0]
	v_pk_mul_f32 v[94:95], v[94:95], v[240:241]
	v_pk_mul_f32 v[96:97], v[96:97], v[242:243]
	v_pk_mul_f32 v[90:91], v[90:91], v[244:245]
	v_pk_mul_f32 v[92:93], v[92:93], v[246:247]
	v_pk_mul_f32 v[86:87], v[86:87], v[248:249]
	v_pk_mul_f32 v[88:89], v[88:89], v[250:251]
	v_pk_mul_f32 v[82:83], v[82:83], v[232:233]
	v_pk_mul_f32 v[84:85], v[84:85], v[234:235]
	global_store_dwordx4 v200, v[94:97], s[62:63] nt
	global_store_dwordx4 v200, v[90:93], s[62:63] offset:16 nt
	global_store_dwordx4 v200, v[86:89], s[62:63] offset:512 nt
	global_store_dwordx4 v200, v[82:85], s[62:63] offset:528 nt
	s_add_u32 s62, s52, 0x30000
	s_addc_u32 s63, s53, 0
	v_pk_mul_f32 v[78:79], v[78:79], v[166:167] op_sel:[0,1] op_sel_hi:[1,1]
	v_pk_mul_f32 v[80:81], v[80:81], v[166:167] op_sel:[0,1] op_sel_hi:[1,1]
	v_pk_mul_f32 v[74:75], v[74:75], v[166:167] op_sel:[0,1] op_sel_hi:[1,1]
	v_pk_mul_f32 v[76:77], v[76:77], v[166:167] op_sel:[0,1] op_sel_hi:[1,1]
	v_pk_mul_f32 v[70:71], v[70:71], v[166:167] op_sel:[0,1] op_sel_hi:[1,1]
	v_pk_mul_f32 v[72:73], v[72:73], v[166:167] op_sel:[0,1] op_sel_hi:[1,1]
	v_pk_mul_f32 v[66:67], v[66:67], v[166:167] op_sel:[0,1] op_sel_hi:[1,1]
	v_pk_mul_f32 v[68:69], v[68:69], v[166:167] op_sel:[0,1] op_sel_hi:[1,1]
	v_pk_mul_f32 v[78:79], v[78:79], v[240:241]
	v_pk_mul_f32 v[80:81], v[80:81], v[242:243]
	v_pk_mul_f32 v[74:75], v[74:75], v[244:245]
	v_pk_mul_f32 v[76:77], v[76:77], v[246:247]
	v_pk_mul_f32 v[70:71], v[70:71], v[248:249]
	v_pk_mul_f32 v[72:73], v[72:73], v[250:251]
	v_pk_mul_f32 v[66:67], v[66:67], v[232:233]
	v_pk_mul_f32 v[68:69], v[68:69], v[234:235]
	global_store_dwordx4 v200, v[78:81], s[62:63] nt
	global_store_dwordx4 v200, v[74:77], s[62:63] offset:16 nt
	global_store_dwordx4 v200, v[70:73], s[62:63] offset:512 nt
	global_store_dwordx4 v200, v[66:69], s[62:63] offset:528 nt
	s_add_u32 s62, s52, 0x80000
	s_addc_u32 s63, s53, 0
	v_pk_mul_f32 v[62:63], v[62:63], v[170:171] op_sel_hi:[1,0]
	v_pk_mul_f32 v[64:65], v[64:65], v[170:171] op_sel_hi:[1,0]
	v_pk_mul_f32 v[58:59], v[58:59], v[170:171] op_sel_hi:[1,0]
	v_pk_mul_f32 v[60:61], v[60:61], v[170:171] op_sel_hi:[1,0]
	v_pk_mul_f32 v[54:55], v[54:55], v[170:171] op_sel_hi:[1,0]
	v_pk_mul_f32 v[56:57], v[56:57], v[170:171] op_sel_hi:[1,0]
	v_pk_mul_f32 v[50:51], v[50:51], v[170:171] op_sel_hi:[1,0]
	v_pk_mul_f32 v[52:53], v[52:53], v[170:171] op_sel_hi:[1,0]
	v_pk_mul_f32 v[62:63], v[62:63], v[240:241]
	v_pk_mul_f32 v[64:65], v[64:65], v[242:243]
	v_pk_mul_f32 v[58:59], v[58:59], v[244:245]
	v_pk_mul_f32 v[60:61], v[60:61], v[246:247]
	v_pk_mul_f32 v[54:55], v[54:55], v[248:249]
	v_pk_mul_f32 v[56:57], v[56:57], v[250:251]
	v_pk_mul_f32 v[50:51], v[50:51], v[232:233]
; __global__ void __launch_bounds__(512, 2) mega(Params P0) {
;     ...
;                 for (int j = 0; j < 16; ++j) { const int i = (ck * 16 + j) * 64 + lane; const int row = i >> 8, c4 = i & 255; const float rstd = rsqrtf(r3[row] * (1.0f / DM) + 1e-6f);
;                     __builtin_nontemporal_store(v[j] * rstd * *(const f32x4*)(fw + 4 * c4), (f32x4*)P.out + i); } } }
	v_pk_mul_f32 v[52:53], v[52:53], v[234:235]
	global_store_dwordx4 v200, v[62:65], s[62:63] nt
	global_store_dwordx4 v200, v[58:61], s[62:63] offset:16 nt
	global_store_dwordx4 v200, v[54:57], s[62:63] offset:512 nt
	global_store_dwordx4 v200, v[50:53], s[62:63] offset:528 nt
	s_add_u32 s62, s52, 0x90000
	s_addc_u32 s63, s53, 0
	v_pk_mul_f32 v[46:47], v[46:47], v[170:171] op_sel:[0,1] op_sel_hi:[1,1]
	v_pk_mul_f32 v[48:49], v[48:49], v[170:171] op_sel:[0,1] op_sel_hi:[1,1]
	v_pk_mul_f32 v[42:43], v[42:43], v[170:171] op_sel:[0,1] op_sel_hi:[1,1]
	v_pk_mul_f32 v[44:45], v[44:45], v[170:171] op_sel:[0,1] op_sel_hi:[1,1]
	v_pk_mul_f32 v[38:39], v[38:39], v[170:171] op_sel:[0,1] op_sel_hi:[1,1]
	v_pk_mul_f32 v[40:41], v[40:41], v[170:171] op_sel:[0,1] op_sel_hi:[1,1]
	v_pk_mul_f32 v[34:35], v[34:35], v[170:171] op_sel:[0,1] op_sel_hi:[1,1]
	v_pk_mul_f32 v[36:37], v[36:37], v[170:171] op_sel:[0,1] op_sel_hi:[1,1]
	v_pk_mul_f32 v[46:47], v[46:47], v[240:241]
	v_pk_mul_f32 v[48:49], v[48:49], v[242:243]
	v_pk_mul_f32 v[42:43], v[42:43], v[244:245]
	v_pk_mul_f32 v[44:45], v[44:45], v[246:247]
	v_pk_mul_f32 v[38:39], v[38:39], v[248:249]
	v_pk_mul_f32 v[40:41], v[40:41], v[250:251]
	v_pk_mul_f32 v[34:35], v[34:35], v[232:233]
	v_pk_mul_f32 v[36:37], v[36:37], v[234:235]
	global_store_dwordx4 v200, v[46:49], s[62:63] nt
	global_store_dwordx4 v200, v[42:45], s[62:63] offset:16 nt
	global_store_dwordx4 v200, v[38:41], s[62:63] offset:512 nt
	global_store_dwordx4 v200, v[34:37], s[62:63] offset:528 nt
	s_add_u32 s62, s52, 0xa0000
	s_addc_u32 s63, s53, 0
	v_pk_mul_f32 v[30:31], v[30:31], v[172:173] op_sel_hi:[1,0]
	v_pk_mul_f32 v[32:33], v[32:33], v[172:173] op_sel_hi:[1,0]
	v_pk_mul_f32 v[26:27], v[26:27], v[172:173] op_sel_hi:[1,0]
	v_pk_mul_f32 v[28:29], v[28:29], v[172:173] op_sel_hi:[1,0]
	v_pk_mul_f32 v[22:23], v[22:23], v[172:173] op_sel_hi:[1,0]
	v_pk_mul_f32 v[24:25], v[24:25], v[172:173] op_sel_hi:[1,0]
	v_pk_mul_f32 v[18:19], v[18:19], v[172:173] op_sel_hi:[1,0]
	v_pk_mul_f32 v[20:21], v[20:21], v[172:173] op_sel_hi:[1,0]
	v_pk_mul_f32 v[30:31], v[30:31], v[240:241]
	v_pk_mul_f32 v[32:33], v[32:33], v[242:243]
	v_pk_mul_f32 v[26:27], v[26:27], v[244:245]
	v_pk_mul_f32 v[28:29], v[28:29], v[246:247]
	v_pk_mul_f32 v[22:23], v[22:23], v[248:249]
	v_pk_mul_f32 v[24:25], v[24:25], v[250:251]
	v_pk_mul_f32 v[18:19], v[18:19], v[232:233]
	v_pk_mul_f32 v[20:21], v[20:21], v[234:235]
	global_store_dwordx4 v200, v[30:33], s[62:63] nt
	global_store_dwordx4 v200, v[26:29], s[62:63] offset:16 nt
	global_store_dwordx4 v200, v[22:25], s[62:63] offset:512 nt
	global_store_dwordx4 v200, v[18:21], s[62:63] offset:528 nt
	s_add_u32 s62, s52, 0xb0000
	s_addc_u32 s63, s53, 0
	v_pk_mul_f32 v[14:15], v[14:15], v[172:173] op_sel:[0,1] op_sel_hi:[1,1]
	v_pk_mul_f32 v[16:17], v[16:17], v[172:173] op_sel:[0,1] op_sel_hi:[1,1]
	v_pk_mul_f32 v[10:11], v[10:11], v[172:173] op_sel:[0,1] op_sel_hi:[1,1]
	v_pk_mul_f32 v[12:13], v[12:13], v[172:173] op_sel:[0,1] op_sel_hi:[1,1]
	v_pk_mul_f32 v[6:7], v[6:7], v[172:173] op_sel:[0,1] op_sel_hi:[1,1]
	v_pk_mul_f32 v[8:9], v[8:9], v[172:173] op_sel:[0,1] op_sel_hi:[1,1]
	v_pk_mul_f32 v[2:3], v[2:3], v[172:173] op_sel:[0,1] op_sel_hi:[1,1]
	v_pk_mul_f32 v[4:5], v[4:5], v[172:173] op_sel:[0,1] op_sel_hi:[1,1]
	v_pk_mul_f32 v[14:15], v[14:15], v[240:241]
	v_pk_mul_f32 v[16:17], v[16:17], v[242:243]
	v_pk_mul_f32 v[10:11], v[10:11], v[244:245]
	v_pk_mul_f32 v[12:13], v[12:13], v[246:247]
	v_pk_mul_f32 v[6:7], v[6:7], v[248:249]
	v_pk_mul_f32 v[8:9], v[8:9], v[250:251]
	v_pk_mul_f32 v[2:3], v[2:3], v[232:233]
	v_pk_mul_f32 v[4:5], v[4:5], v[234:235]
	global_store_dwordx4 v200, v[14:17], s[62:63] nt
	global_store_dwordx4 v200, v[10:13], s[62:63] offset:16 nt
	global_store_dwordx4 v200, v[6:9], s[62:63] offset:512 nt
	global_store_dwordx4 v200, v[2:5], s[62:63] offset:528 nt
	s_mov_b64 s[2:3], 0
	s_branch .LBB0_766

; __global__ void __launch_bounds__(512, 2) mega(Params P0) {
;     ...
;         if (ph < ph_hi) {
;             if (ph_lo < 0) grid.sync();
;             xcd_barrier(xb);
;         }
.LBB0_1065:
	v_readlane_b32 s18, v254, 2
	v_readlane_b32 s20, v254, 4
	v_readlane_b32 s40, v254, 22
	v_readlane_b32 s42, v254, 24
	v_readlane_b32 s44, v254, 26
	v_readlane_b32 s46, v254, 28
	v_readlane_b32 s48, v254, 30
	v_readlane_b32 s50, v254, 32
	s_min_i32 s2, s81, 10
	s_cmp_ge_i32 s80, s2
	s_mov_b64 s[2:3], -1
	v_readlane_b32 s19, v254, 3
	v_readlane_b32 s21, v254, 5
	v_readlane_b32 s41, v254, 23
	v_readlane_b32 s43, v254, 25
	v_readlane_b32 s45, v254, 27
	v_readlane_b32 s47, v254, 29
	v_readlane_b32 s49, v254, 31
	v_readlane_b32 s51, v254, 33
	v_writelane_b32 v255, s26, 24
	s_cbranch_scc0 .LBB0_1066
	s_getpc_b64 s[98:99]
